# gdn_prep stage C: 2x2 blocked forward substitution - rows 0-31 and 32-63 by substitution, the 32x32 off-diagonal block via exact-f32 MFMA (v_mfma_f32_32x32x2_f32) with permlane32_swap layout changes (
# speedup vs baseline: 1.0048x; 1.0048x over previous
; __device__ __forceinline__ float bf2f(bf16 v) { return __uint_as_float(((unsigned)v) << 16); }
; #define GDN_LOADROW(buf, rr_, i_) do { _Pragma("unroll") for (int j4 = 0; j4 < ((i_) + 3) / 4; ++j4) buf[j4] = *(const f32x4*)(Lm + (i_) * GP_LSTR + 4 * j4); rr_ = bf2f(*(const bf16*)(xsrc + (i_) * GP_STR * 2)) * scl[i_]; } while (0)
; template <int STRIP> __device__ __forceinline__ void ph_gdn_prep_fast(const bf16* __restrict__ proj, const float* __restrict__ small, const float* __restrict__ conv_w, const float* __restrict__ a_log, const float* __restrict__ dt_bias, ...
;     ...
;             const int cs = wave >> 2, ci = 2 * pair + cs;
;             unsigned char* L = lds_dyn + cs * GP_CHUNK; const float* sgc = (const float*)(L + GP_SC); const float* sbeta = sgc + 64; const float* segc = sgc + 128; const float* sekd = sgc + 192;
;             const int c = (wave & 3) * 64 + lane; const bool isw = c >= 128; const int cc = c & 127;
;             const unsigned char* xsrc = L + (isw ? GP_K : GP_V) + cc * 2;
;             const float* Lm = (const float*)(L + GP_L);
;             float U[64];
;             const float* scl = isw ? (sgc + 256) : sbeta;
;             f32x4 bA[16], bB[16]; float rA, rB = 0.f;
;             rA = bf2f(*(const bf16*)xsrc) * scl[0];
;     ...
; #pragma unroll
;             for (int i = 0; i < 64; i += 2) {
;                 GDN_LOADROW(bB, rB, i + 1);
;                 GDN_ROW(bA, rA, i);
;                 if (i + 2 < 64) GDN_LOADROW(bA, rA, i + 2);
;                 GDN_ROW(bB, rB, i + 1);
;             }
.LBB0_1303:
	s_or_b64 exec, exec, s[8:9]
	v_ashrrev_i32_e32 v8, 8, v78
	s_mov_b32 s0, 0x11500
	v_and_b32_e32 v4, 0x80, v78
	v_and_b32_e32 v2, 0x80, v78
	v_mad_i32_i24 v10, v8, s0, 0
	v_cmp_ne_u32_e32 vcc, 0, v2
	v_and_b32_e32 v2, 0x7f, v78
	v_cmp_eq_u32_e64 s[0:1], 0, v4
	v_mov_b32_e32 v4, 0x8800
	v_lshlrev_b32_e32 v18, 1, v2
	v_cndmask_b32_e64 v4, v236, v4, s[0:1]
	s_waitcnt lgkmcnt(0)
	s_barrier
	v_add3_u32 v123, v10, v4, v18
	v_mov_b32_e32 v126, 0x11400
	v_mov_b32_e32 v127, 0x11100
	v_and_b32_e32 v125, 3, v78
	v_cndmask_b32_e64 v126, v126, v127, s[0:1]
	v_lshlrev_b32_e32 v125, 3, v125
	v_add_u32_e32 v124, v10, v126
	v_add_u32_e32 v125, 0xcc00, v125
	v_add_u32_e32 v125, v10, v125
	v_and_b32_e32 v130, 31, v78
	v_bfe_u32 v127, v78, 5, 1
	v_add_u32_e32 v130, 32, v130
	v_mul_u32_u24_e32 v130, 0x110, v130
	v_lshl_add_u32 v130, v127, 2, v130
	v_add_u32_e32 v130, 0xcc00, v130
	v_add_u32_e32 v130, v10, v130
	ds_read_b32 v172, v130 offset:0
	ds_read_b32 v173, v130 offset:8
	ds_read_b32 v174, v130 offset:16
	ds_read_b32 v175, v130 offset:24
	ds_read_b32 v176, v130 offset:32
	ds_read_b32 v177, v130 offset:40
	ds_read_b32 v178, v130 offset:48
	ds_read_b32 v179, v130 offset:56
	ds_read_b32 v222, v130 offset:64
	ds_read_b32 v223, v130 offset:72
	ds_read_b32 v224, v130 offset:80
	ds_read_b32 v225, v130 offset:88
	ds_read_b32 v226, v130 offset:96
	ds_read_b32 v227, v130 offset:104
	ds_read_b32 v228, v130 offset:112
	ds_read_b32 v229, v130 offset:120
	v_mov_b32_e32 v244, 0
	v_mov_b32_e32 v245, 0
	v_mov_b32_e32 v246, 0
	v_mov_b32_e32 v247, 0
	v_mov_b32_e32 v248, 0
	v_mov_b32_e32 v249, 0
	v_mov_b32_e32 v250, 0
	v_mov_b32_e32 v251, 0
	v_mov_b32_e32 v252, 0
	v_mov_b32_e32 v253, 0
	v_mov_b32_e32 v126, 0
	v_mov_b32_e32 v127, 0
	ds_read_b32 v208, v124 offset:0
	ds_read_u16_d16_hi v244, v123 offset:0
	ds_read_b64 v[186:187], v125 offset:272
	ds_read_b32 v209, v124 offset:4
	ds_read_u16_d16_hi v245, v123 offset:272
	ds_read_b64 v[188:189], v125 offset:544
	ds_read_b32 v210, v124 offset:8
	ds_read_u16_d16_hi v246, v123 offset:544
	ds_read_b64 v[190:191], v125 offset:816
	ds_read_b32 v211, v124 offset:12
	ds_read_u16_d16_hi v247, v123 offset:816
	ds_read_b64 v[192:193], v125 offset:1088
	ds_read_b32 v212, v124 offset:16
	ds_read_u16_d16_hi v248, v123 offset:1088
	ds_read_b64 v[194:195], v125 offset:1360
	ds_read_b32 v213, v124 offset:20
	ds_read_u16_d16_hi v249, v123 offset:1360
	ds_read_b64 v[196:197], v125 offset:1632
	ds_read_b32 v214, v124 offset:24
	ds_read_u16_d16_hi v250, v123 offset:1632
	ds_read_b64 v[198:199], v125 offset:1904
	ds_read_b32 v215, v124 offset:28
	ds_read_u16_d16_hi v251, v123 offset:1904
	ds_read_b64 v[200:201], v125 offset:2176
	ds_read_b32 v216, v124 offset:32
	ds_read_u16_d16_hi v252, v123 offset:2176
	ds_read_b64 v[202:203], v125 offset:2448
	ds_read_b64 v[204:205], v125 offset:2480
	ds_read_b32 v217, v124 offset:36
	ds_read_u16_d16_hi v253, v123 offset:2448
	ds_read_b64 v[206:207], v125 offset:2720
	ds_read_b64 v[164:165], v125 offset:2752
	ds_read_b32 v218, v124 offset:40
	ds_read_u16_d16_hi v126, v123 offset:2720
	s_waitcnt lgkmcnt(15)
	v_fma_f32 v4, v208, v244, 0
	s_waitcnt lgkmcnt(15)
	v_mul_f32_dpp v120, v186, v4 quad_perm:[0,0,0,0] row_mask:0xf bank_mask:0xf
	v_fma_f32 v116, v209, v245, -v120
	v_add_f32_e32 v5, 0, v116
	s_waitcnt lgkmcnt(15)
	v_mul_f32_dpp v120, v188, v4 quad_perm:[0,0,0,0] row_mask:0xf bank_mask:0xf
	v_fma_f32 v116, v210, v246, -v120
	v_mul_f32_dpp v117, -v189, v5 quad_perm:[0,0,0,0] row_mask:0xf bank_mask:0xf
	v_add_f32_e32 v6, v117, v116
	s_waitcnt lgkmcnt(15)
	v_mul_f32_dpp v120, v190, v4 quad_perm:[0,0,0,0] row_mask:0xf bank_mask:0xf
	v_fma_f32 v116, v211, v247, -v120
	v_mul_f32_dpp v117, -v191, v5 quad_perm:[0,0,0,0] row_mask:0xf bank_mask:0xf
	v_mul_f32_dpp v118, -v190, v6 quad_perm:[1,1,1,1] row_mask:0xf bank_mask:0xf
	ds_read_b64 v[166:167], v125 offset:2992
	v_add_f32_e32 v121, v117, v116
	v_add_f32_e32 v12, v118, v121
	s_waitcnt lgkmcnt(15)
	v_mul_f32_dpp v120, v192, v4 quad_perm:[0,0,0,0] row_mask:0xf bank_mask:0xf
	v_fma_f32 v116, v212, v248, -v120
	v_mul_f32_dpp v117, -v193, v5 quad_perm:[0,0,0,0] row_mask:0xf bank_mask:0xf
	v_mul_f32_dpp v118, -v192, v6 quad_perm:[1,1,1,1] row_mask:0xf bank_mask:0xf
	v_mul_f32_dpp v119, -v193, v12 quad_perm:[1,1,1,1] row_mask:0xf bank_mask:0xf
	ds_read_b64 v[168:169], v125 offset:3024
	v_add_f32_e32 v121, v117, v116
	v_add_f32_e32 v122, v118, v119
	v_add_f32_e32 v7, v122, v121
	s_waitcnt lgkmcnt(15)
	v_mul_f32_dpp v120, v194, v4 quad_perm:[0,0,0,0] row_mask:0xf bank_mask:0xf
	v_fma_f32 v116, v213, v249, -v120
	v_mul_f32_dpp v117, -v195, v5 quad_perm:[0,0,0,0] row_mask:0xf bank_mask:0xf
	v_mul_f32_dpp v118, -v194, v6 quad_perm:[1,1,1,1] row_mask:0xf bank_mask:0xf
	v_mul_f32_dpp v119, -v195, v12 quad_perm:[1,1,1,1] row_mask:0xf bank_mask:0xf
	ds_read_b32 v219, v124 offset:44
	v_fmac_f32_dpp v116, -v194, v7 quad_perm:[2,2,2,2] row_mask:0xf bank_mask:0xf
	v_add_f32_e32 v121, v117, v116
	v_add_f32_e32 v122, v118, v119
	v_add_f32_e32 v13, v122, v121
	s_waitcnt lgkmcnt(15)
	v_mul_f32_dpp v120, v196, v4 quad_perm:[0,0,0,0] row_mask:0xf bank_mask:0xf
	v_fma_f32 v116, v214, v250, -v120
	v_mul_f32_dpp v117, -v197, v5 quad_perm:[0,0,0,0] row_mask:0xf bank_mask:0xf
	v_mul_f32_dpp v118, -v196, v6 quad_perm:[1,1,1,1] row_mask:0xf bank_mask:0xf
	ds_read_u16_d16_hi v127, v123 offset:2992
	v_mul_f32_dpp v119, -v197, v12 quad_perm:[1,1,1,1] row_mask:0xf bank_mask:0xf
	v_fmac_f32_dpp v116, -v196, v7 quad_perm:[2,2,2,2] row_mask:0xf bank_mask:0xf
	v_fmac_f32_dpp v117, -v197, v13 quad_perm:[2,2,2,2] row_mask:0xf bank_mask:0xf
	ds_read_b64 v[170:171], v125 offset:3264
	v_add_f32_e32 v121, v117, v116
	v_add_f32_e32 v122, v118, v119
	v_add_f32_e32 v14, v122, v121
	s_waitcnt lgkmcnt(15)
; #define GDN_LOADROW(buf, rr_, i_) do { _Pragma("unroll") for (int j4 = 0; j4 < ((i_) + 3) / 4; ++j4) buf[j4] = *(const f32x4*)(Lm + (i_) * GP_LSTR + 4 * j4); rr_ = bf2f(*(const bf16*)(xsrc + (i_) * GP_STR * 2)) * scl[i_]; } while (0)
; template <int STRIP> __device__ __forceinline__ void ph_gdn_prep_fast(const bf16* __restrict__ proj, const float* __restrict__ small, const float* __restrict__ conv_w, const float* __restrict__ a_log, const float* __restrict__ dt_bias, ...
;     ...
; #pragma unroll
;             for (int i = 0; i < 64; i += 2) {
;                 GDN_LOADROW(bB, rB, i + 1);
;                 GDN_ROW(bA, rA, i);
;                 if (i + 2 < 64) GDN_LOADROW(bA, rA, i + 2);
;                 GDN_ROW(bB, rB, i + 1);
;             }
	v_mul_f32_dpp v120, v198, v4 quad_perm:[0,0,0,0] row_mask:0xf bank_mask:0xf
	v_fma_f32 v116, v215, v251, -v120
	v_mul_f32_dpp v117, -v199, v5 quad_perm:[0,0,0,0] row_mask:0xf bank_mask:0xf
	v_mul_f32_dpp v118, -v198, v6 quad_perm:[1,1,1,1] row_mask:0xf bank_mask:0xf
	v_mul_f32_dpp v119, -v199, v12 quad_perm:[1,1,1,1] row_mask:0xf bank_mask:0xf
	ds_read_b64 v[132:133], v125 offset:3296
	v_fmac_f32_dpp v116, -v198, v7 quad_perm:[2,2,2,2] row_mask:0xf bank_mask:0xf
	v_fmac_f32_dpp v117, -v199, v13 quad_perm:[2,2,2,2] row_mask:0xf bank_mask:0xf
	v_fmac_f32_dpp v118, -v198, v14 quad_perm:[3,3,3,3] row_mask:0xf bank_mask:0xf
	ds_read_b32 v220, v124 offset:48
	v_add_f32_e32 v121, v117, v116
	v_add_f32_e32 v122, v118, v119
	v_add_f32_e32 v15, v122, v121
	s_waitcnt lgkmcnt(15)
	v_mul_f32_dpp v120, v200, v4 quad_perm:[0,0,0,0] row_mask:0xf bank_mask:0xf
	v_fma_f32 v116, v216, v252, -v120
	v_mul_f32_dpp v117, -v201, v5 quad_perm:[0,0,0,0] row_mask:0xf bank_mask:0xf
	v_mul_f32_dpp v118, -v200, v6 quad_perm:[1,1,1,1] row_mask:0xf bank_mask:0xf
	v_mul_f32_dpp v119, -v201, v12 quad_perm:[1,1,1,1] row_mask:0xf bank_mask:0xf
	ds_read_u16_d16_hi v244, v123 offset:3264
	v_fmac_f32_dpp v116, -v200, v7 quad_perm:[2,2,2,2] row_mask:0xf bank_mask:0xf
	v_fmac_f32_dpp v117, -v201, v13 quad_perm:[2,2,2,2] row_mask:0xf bank_mask:0xf
	v_fmac_f32_dpp v118, -v200, v14 quad_perm:[3,3,3,3] row_mask:0xf bank_mask:0xf
	ds_read_b64 v[134:135], v125 offset:3536
	v_fmac_f32_dpp v119, -v201, v15 quad_perm:[3,3,3,3] row_mask:0xf bank_mask:0xf
	v_add_f32_e32 v121, v117, v116
	v_add_f32_e32 v122, v118, v119
	v_add_f32_e32 v16, v122, v121
	s_waitcnt lgkmcnt(13)
	v_mul_f32_dpp v120, v202, v4 quad_perm:[0,0,0,0] row_mask:0xf bank_mask:0xf
	v_fma_f32 v116, v217, v253, -v120
	v_mul_f32_dpp v117, -v203, v5 quad_perm:[0,0,0,0] row_mask:0xf bank_mask:0xf
	v_mul_f32_dpp v118, -v202, v6 quad_perm:[1,1,1,1] row_mask:0xf bank_mask:0xf
	ds_read_b64 v[136:137], v125 offset:3568
	v_mul_f32_dpp v119, -v203, v12 quad_perm:[1,1,1,1] row_mask:0xf bank_mask:0xf
	v_fmac_f32_dpp v116, -v202, v7 quad_perm:[2,2,2,2] row_mask:0xf bank_mask:0xf
	v_fmac_f32_dpp v117, -v203, v13 quad_perm:[2,2,2,2] row_mask:0xf bank_mask:0xf
	ds_read_b32 v221, v124 offset:52
	v_fmac_f32_dpp v118, -v202, v14 quad_perm:[3,3,3,3] row_mask:0xf bank_mask:0xf
	v_fmac_f32_dpp v119, -v203, v15 quad_perm:[3,3,3,3] row_mask:0xf bank_mask:0xf
	v_fmac_f32_dpp v116, -v204, v16 quad_perm:[0,0,0,0] row_mask:0xf bank_mask:0xf
	ds_read_u16_d16_hi v245, v123 offset:3536
	v_add_f32_e32 v121, v117, v116
	v_add_f32_e32 v122, v118, v119
	v_add_f32_e32 v17, v122, v121
	s_waitcnt lgkmcnt(12)
	v_mul_f32_dpp v120, v206, v4 quad_perm:[0,0,0,0] row_mask:0xf bank_mask:0xf
	v_fma_f32 v116, v218, v126, -v120
	v_mul_f32_dpp v117, -v207, v5 quad_perm:[0,0,0,0] row_mask:0xf bank_mask:0xf
	v_mul_f32_dpp v118, -v206, v6 quad_perm:[1,1,1,1] row_mask:0xf bank_mask:0xf
	v_mul_f32_dpp v119, -v207, v12 quad_perm:[1,1,1,1] row_mask:0xf bank_mask:0xf
	ds_read_b64 v[138:139], v125 offset:3808
	v_fmac_f32_dpp v116, -v206, v7 quad_perm:[2,2,2,2] row_mask:0xf bank_mask:0xf
	v_fmac_f32_dpp v117, -v207, v13 quad_perm:[2,2,2,2] row_mask:0xf bank_mask:0xf
	v_fmac_f32_dpp v118, -v206, v14 quad_perm:[3,3,3,3] row_mask:0xf bank_mask:0xf
	ds_read_b64 v[140:141], v125 offset:3840
	v_fmac_f32_dpp v119, -v207, v15 quad_perm:[3,3,3,3] row_mask:0xf bank_mask:0xf
	v_fmac_f32_dpp v116, -v164, v16 quad_perm:[0,0,0,0] row_mask:0xf bank_mask:0xf
	v_fmac_f32_dpp v117, -v165, v17 quad_perm:[0,0,0,0] row_mask:0xf bank_mask:0xf
	ds_read_b32 v181, v124 offset:56
	v_add_f32_e32 v121, v117, v116
	v_add_f32_e32 v122, v118, v119
	v_add_f32_e32 v19, v122, v121
	s_waitcnt lgkmcnt(11)
	v_mul_f32_dpp v120, v166, v4 quad_perm:[0,0,0,0] row_mask:0xf bank_mask:0xf
	v_fma_f32 v116, v219, v127, -v120
	v_mul_f32_dpp v117, -v167, v5 quad_perm:[0,0,0,0] row_mask:0xf bank_mask:0xf
	v_mul_f32_dpp v118, -v166, v6 quad_perm:[1,1,1,1] row_mask:0xf bank_mask:0xf
	v_mul_f32_dpp v119, -v167, v12 quad_perm:[1,1,1,1] row_mask:0xf bank_mask:0xf
	ds_read_u16_d16_hi v246, v123 offset:3808
	v_fmac_f32_dpp v116, -v166, v7 quad_perm:[2,2,2,2] row_mask:0xf bank_mask:0xf
	v_fmac_f32_dpp v117, -v167, v13 quad_perm:[2,2,2,2] row_mask:0xf bank_mask:0xf
	v_fmac_f32_dpp v118, -v166, v14 quad_perm:[3,3,3,3] row_mask:0xf bank_mask:0xf
	ds_read_b64 v[142:143], v125 offset:4080
	v_fmac_f32_dpp v119, -v167, v15 quad_perm:[3,3,3,3] row_mask:0xf bank_mask:0xf
	v_fmac_f32_dpp v116, -v168, v16 quad_perm:[0,0,0,0] row_mask:0xf bank_mask:0xf
	v_fmac_f32_dpp v117, -v169, v17 quad_perm:[0,0,0,0] row_mask:0xf bank_mask:0xf
	ds_read_b64 v[144:145], v125 offset:4112
	v_fmac_f32_dpp v118, -v168, v19 quad_perm:[1,1,1,1] row_mask:0xf bank_mask:0xf
	v_add_f32_e32 v121, v117, v116
	v_add_f32_e32 v122, v118, v119
	v_add_f32_e32 v20, v122, v121
	s_waitcnt lgkmcnt(10)
	v_mul_f32_dpp v120, v170, v4 quad_perm:[0,0,0,0] row_mask:0xf bank_mask:0xf
	v_fma_f32 v116, v220, v244, -v120
	v_mul_f32_dpp v117, -v171, v5 quad_perm:[0,0,0,0] row_mask:0xf bank_mask:0xf
	v_mul_f32_dpp v118, -v170, v6 quad_perm:[1,1,1,1] row_mask:0xf bank_mask:0xf
	ds_read_b32 v182, v124 offset:60
	v_mul_f32_dpp v119, -v171, v12 quad_perm:[1,1,1,1] row_mask:0xf bank_mask:0xf
	v_fmac_f32_dpp v116, -v170, v7 quad_perm:[2,2,2,2] row_mask:0xf bank_mask:0xf
	v_fmac_f32_dpp v117, -v171, v13 quad_perm:[2,2,2,2] row_mask:0xf bank_mask:0xf
	ds_read_u16_d16_hi v247, v123 offset:4080
	v_fmac_f32_dpp v118, -v170, v14 quad_perm:[3,3,3,3] row_mask:0xf bank_mask:0xf
	v_fmac_f32_dpp v119, -v171, v15 quad_perm:[3,3,3,3] row_mask:0xf bank_mask:0xf
	v_fmac_f32_dpp v116, -v132, v16 quad_perm:[0,0,0,0] row_mask:0xf bank_mask:0xf
	ds_read_b64 v[146:147], v125 offset:4352
	v_fmac_f32_dpp v117, -v133, v17 quad_perm:[0,0,0,0] row_mask:0xf bank_mask:0xf
	v_fmac_f32_dpp v118, -v132, v19 quad_perm:[1,1,1,1] row_mask:0xf bank_mask:0xf
	v_fmac_f32_dpp v119, -v133, v20 quad_perm:[1,1,1,1] row_mask:0xf bank_mask:0xf
	ds_read_b64 v[148:149], v125 offset:4384
	v_add_f32_e32 v121, v117, v116
	v_add_f32_e32 v122, v118, v119
	v_add_f32_e32 v21, v122, v121
	s_waitcnt lgkmcnt(10)
; #define GDN_LOADROW(buf, rr_, i_) do { _Pragma("unroll") for (int j4 = 0; j4 < ((i_) + 3) / 4; ++j4) buf[j4] = *(const f32x4*)(Lm + (i_) * GP_LSTR + 4 * j4); rr_ = bf2f(*(const bf16*)(xsrc + (i_) * GP_STR * 2)) * scl[i_]; } while (0)
; template <int STRIP> __device__ __forceinline__ void ph_gdn_prep_fast(const bf16* __restrict__ proj, const float* __restrict__ small, const float* __restrict__ conv_w, const float* __restrict__ a_log, const float* __restrict__ dt_bias, ...
;     ...
; #pragma unroll
;             for (int i = 0; i < 64; i += 2) {
;                 GDN_LOADROW(bB, rB, i + 1);
;                 GDN_ROW(bA, rA, i);
;                 if (i + 2 < 64) GDN_LOADROW(bA, rA, i + 2);
;                 GDN_ROW(bB, rB, i + 1);
;             }
	v_mul_f32_dpp v120, v134, v4 quad_perm:[0,0,0,0] row_mask:0xf bank_mask:0xf
	v_fma_f32 v116, v221, v245, -v120
	v_mul_f32_dpp v117, -v135, v5 quad_perm:[0,0,0,0] row_mask:0xf bank_mask:0xf
	v_mul_f32_dpp v118, -v134, v6 quad_perm:[1,1,1,1] row_mask:0xf bank_mask:0xf
	v_mul_f32_dpp v119, -v135, v12 quad_perm:[1,1,1,1] row_mask:0xf bank_mask:0xf
	ds_read_b32 v183, v124 offset:64
	v_fmac_f32_dpp v116, -v134, v7 quad_perm:[2,2,2,2] row_mask:0xf bank_mask:0xf
	v_fmac_f32_dpp v117, -v135, v13 quad_perm:[2,2,2,2] row_mask:0xf bank_mask:0xf
	v_fmac_f32_dpp v118, -v134, v14 quad_perm:[3,3,3,3] row_mask:0xf bank_mask:0xf
	ds_read_u16_d16_hi v248, v123 offset:4352
	v_fmac_f32_dpp v119, -v135, v15 quad_perm:[3,3,3,3] row_mask:0xf bank_mask:0xf
	v_fmac_f32_dpp v116, -v136, v16 quad_perm:[0,0,0,0] row_mask:0xf bank_mask:0xf
	v_fmac_f32_dpp v117, -v137, v17 quad_perm:[0,0,0,0] row_mask:0xf bank_mask:0xf
	ds_read_b64 v[150:151], v125 offset:4624
	v_fmac_f32_dpp v118, -v136, v19 quad_perm:[1,1,1,1] row_mask:0xf bank_mask:0xf
	v_fmac_f32_dpp v119, -v137, v20 quad_perm:[1,1,1,1] row_mask:0xf bank_mask:0xf
	v_fmac_f32_dpp v116, -v136, v21 quad_perm:[2,2,2,2] row_mask:0xf bank_mask:0xf
	ds_read_b64 v[152:153], v125 offset:4656
	v_add_f32_e32 v121, v117, v116
	v_add_f32_e32 v122, v118, v119
	v_add_f32_e32 v22, v122, v121
	s_waitcnt lgkmcnt(10)
	v_mul_f32_dpp v120, v138, v4 quad_perm:[0,0,0,0] row_mask:0xf bank_mask:0xf
	v_fma_f32 v116, v181, v246, -v120
	v_mul_f32_dpp v117, -v139, v5 quad_perm:[0,0,0,0] row_mask:0xf bank_mask:0xf
	v_mul_f32_dpp v118, -v138, v6 quad_perm:[1,1,1,1] row_mask:0xf bank_mask:0xf
	v_mul_f32_dpp v119, -v139, v12 quad_perm:[1,1,1,1] row_mask:0xf bank_mask:0xf
	ds_read_b64 v[154:155], v125 offset:4688
	v_fmac_f32_dpp v116, -v138, v7 quad_perm:[2,2,2,2] row_mask:0xf bank_mask:0xf
	v_fmac_f32_dpp v117, -v139, v13 quad_perm:[2,2,2,2] row_mask:0xf bank_mask:0xf
	v_fmac_f32_dpp v118, -v138, v14 quad_perm:[3,3,3,3] row_mask:0xf bank_mask:0xf
	ds_read_b32 v185, v124 offset:68
	v_fmac_f32_dpp v119, -v139, v15 quad_perm:[3,3,3,3] row_mask:0xf bank_mask:0xf
	v_fmac_f32_dpp v116, -v140, v16 quad_perm:[0,0,0,0] row_mask:0xf bank_mask:0xf
	v_fmac_f32_dpp v117, -v141, v17 quad_perm:[0,0,0,0] row_mask:0xf bank_mask:0xf
	ds_read_u16_d16_hi v249, v123 offset:4624
	v_fmac_f32_dpp v118, -v140, v19 quad_perm:[1,1,1,1] row_mask:0xf bank_mask:0xf
	v_fmac_f32_dpp v119, -v141, v20 quad_perm:[1,1,1,1] row_mask:0xf bank_mask:0xf
	v_fmac_f32_dpp v116, -v140, v21 quad_perm:[2,2,2,2] row_mask:0xf bank_mask:0xf
	ds_read_b64 v[156:157], v125 offset:4896
	v_fmac_f32_dpp v117, -v141, v22 quad_perm:[2,2,2,2] row_mask:0xf bank_mask:0xf
	v_add_f32_e32 v121, v117, v116
	v_add_f32_e32 v122, v118, v119
	v_add_f32_e32 v23, v122, v121
	s_waitcnt lgkmcnt(10)
	v_mul_f32_dpp v120, v142, v4 quad_perm:[0,0,0,0] row_mask:0xf bank_mask:0xf
	v_fma_f32 v116, v182, v247, -v120
	v_mul_f32_dpp v117, -v143, v5 quad_perm:[0,0,0,0] row_mask:0xf bank_mask:0xf
	v_mul_f32_dpp v118, -v142, v6 quad_perm:[1,1,1,1] row_mask:0xf bank_mask:0xf
	ds_read_b64 v[158:159], v125 offset:4928
	v_mul_f32_dpp v119, -v143, v12 quad_perm:[1,1,1,1] row_mask:0xf bank_mask:0xf
	v_fmac_f32_dpp v116, -v142, v7 quad_perm:[2,2,2,2] row_mask:0xf bank_mask:0xf
	v_fmac_f32_dpp v117, -v143, v13 quad_perm:[2,2,2,2] row_mask:0xf bank_mask:0xf
	ds_read_b64 v[160:161], v125 offset:4960
	v_fmac_f32_dpp v118, -v142, v14 quad_perm:[3,3,3,3] row_mask:0xf bank_mask:0xf
	v_fmac_f32_dpp v119, -v143, v15 quad_perm:[3,3,3,3] row_mask:0xf bank_mask:0xf
	v_fmac_f32_dpp v116, -v144, v16 quad_perm:[0,0,0,0] row_mask:0xf bank_mask:0xf
	ds_read_b32 v208, v124 offset:72
	v_fmac_f32_dpp v117, -v145, v17 quad_perm:[0,0,0,0] row_mask:0xf bank_mask:0xf
	v_fmac_f32_dpp v118, -v144, v19 quad_perm:[1,1,1,1] row_mask:0xf bank_mask:0xf
	v_fmac_f32_dpp v119, -v145, v20 quad_perm:[1,1,1,1] row_mask:0xf bank_mask:0xf
	ds_read_u16_d16_hi v250, v123 offset:4896
	v_fmac_f32_dpp v116, -v144, v21 quad_perm:[2,2,2,2] row_mask:0xf bank_mask:0xf
	v_fmac_f32_dpp v117, -v145, v22 quad_perm:[2,2,2,2] row_mask:0xf bank_mask:0xf
	v_fmac_f32_dpp v118, -v144, v23 quad_perm:[3,3,3,3] row_mask:0xf bank_mask:0xf
	ds_read_b64 v[162:163], v125 offset:5168
	v_add_f32_e32 v121, v117, v116
	v_add_f32_e32 v122, v118, v119
	v_add_f32_e32 v24, v122, v121
	s_waitcnt lgkmcnt(11)
	v_mul_f32_dpp v120, v146, v4 quad_perm:[0,0,0,0] row_mask:0xf bank_mask:0xf
	v_fma_f32 v116, v183, v248, -v120
	v_mul_f32_dpp v117, -v147, v5 quad_perm:[0,0,0,0] row_mask:0xf bank_mask:0xf
	v_mul_f32_dpp v118, -v146, v6 quad_perm:[1,1,1,1] row_mask:0xf bank_mask:0xf
	v_mul_f32_dpp v119, -v147, v12 quad_perm:[1,1,1,1] row_mask:0xf bank_mask:0xf
	ds_read_b64 v[186:187], v125 offset:5200
	v_fmac_f32_dpp v116, -v146, v7 quad_perm:[2,2,2,2] row_mask:0xf bank_mask:0xf
	v_fmac_f32_dpp v117, -v147, v13 quad_perm:[2,2,2,2] row_mask:0xf bank_mask:0xf
	v_fmac_f32_dpp v118, -v146, v14 quad_perm:[3,3,3,3] row_mask:0xf bank_mask:0xf
	ds_read_b64 v[188:189], v125 offset:5232
	v_fmac_f32_dpp v119, -v147, v15 quad_perm:[3,3,3,3] row_mask:0xf bank_mask:0xf
	v_fmac_f32_dpp v116, -v148, v16 quad_perm:[0,0,0,0] row_mask:0xf bank_mask:0xf
	v_fmac_f32_dpp v117, -v149, v17 quad_perm:[0,0,0,0] row_mask:0xf bank_mask:0xf
	ds_read_b32 v209, v124 offset:76
	v_fmac_f32_dpp v118, -v148, v19 quad_perm:[1,1,1,1] row_mask:0xf bank_mask:0xf
	v_fmac_f32_dpp v119, -v149, v20 quad_perm:[1,1,1,1] row_mask:0xf bank_mask:0xf
	v_fmac_f32_dpp v116, -v148, v21 quad_perm:[2,2,2,2] row_mask:0xf bank_mask:0xf
	ds_read_u16_d16_hi v251, v123 offset:5168
	v_fmac_f32_dpp v117, -v149, v22 quad_perm:[2,2,2,2] row_mask:0xf bank_mask:0xf
	v_fmac_f32_dpp v118, -v148, v23 quad_perm:[3,3,3,3] row_mask:0xf bank_mask:0xf
	v_fmac_f32_dpp v119, -v149, v24 quad_perm:[3,3,3,3] row_mask:0xf bank_mask:0xf
	ds_read_b64 v[190:191], v125 offset:5440
	v_add_f32_e32 v121, v117, v116
	v_add_f32_e32 v122, v118, v119
	v_add_f32_e32 v25, v122, v121
	s_waitcnt lgkmcnt(11)
; #define GDN_LOADROW(buf, rr_, i_) do { _Pragma("unroll") for (int j4 = 0; j4 < ((i_) + 3) / 4; ++j4) buf[j4] = *(const f32x4*)(Lm + (i_) * GP_LSTR + 4 * j4); rr_ = bf2f(*(const bf16*)(xsrc + (i_) * GP_STR * 2)) * scl[i_]; } while (0)
; template <int STRIP> __device__ __forceinline__ void ph_gdn_prep_fast(const bf16* __restrict__ proj, const float* __restrict__ small, const float* __restrict__ conv_w, const float* __restrict__ a_log, const float* __restrict__ dt_bias, ...
;     ...
; #pragma unroll
;             for (int i = 0; i < 64; i += 2) {
;                 GDN_LOADROW(bB, rB, i + 1);
;                 GDN_ROW(bA, rA, i);
;                 if (i + 2 < 64) GDN_LOADROW(bA, rA, i + 2);
;                 GDN_ROW(bB, rB, i + 1);
;             }
	v_mul_f32_dpp v120, v150, v4 quad_perm:[0,0,0,0] row_mask:0xf bank_mask:0xf
	v_fma_f32 v116, v185, v249, -v120
	v_mul_f32_dpp v117, -v151, v5 quad_perm:[0,0,0,0] row_mask:0xf bank_mask:0xf
	v_mul_f32_dpp v118, -v150, v6 quad_perm:[1,1,1,1] row_mask:0xf bank_mask:0xf
	v_mul_f32_dpp v119, -v151, v12 quad_perm:[1,1,1,1] row_mask:0xf bank_mask:0xf
	ds_read_b64 v[192:193], v125 offset:5472
	v_fmac_f32_dpp v116, -v150, v7 quad_perm:[2,2,2,2] row_mask:0xf bank_mask:0xf
	v_fmac_f32_dpp v117, -v151, v13 quad_perm:[2,2,2,2] row_mask:0xf bank_mask:0xf
	v_fmac_f32_dpp v118, -v150, v14 quad_perm:[3,3,3,3] row_mask:0xf bank_mask:0xf
	ds_read_b64 v[194:195], v125 offset:5504
	v_fmac_f32_dpp v119, -v151, v15 quad_perm:[3,3,3,3] row_mask:0xf bank_mask:0xf
	v_fmac_f32_dpp v116, -v152, v16 quad_perm:[0,0,0,0] row_mask:0xf bank_mask:0xf
	v_fmac_f32_dpp v117, -v153, v17 quad_perm:[0,0,0,0] row_mask:0xf bank_mask:0xf
	ds_read_b32 v210, v124 offset:80
	v_fmac_f32_dpp v118, -v152, v19 quad_perm:[1,1,1,1] row_mask:0xf bank_mask:0xf
	v_fmac_f32_dpp v119, -v153, v20 quad_perm:[1,1,1,1] row_mask:0xf bank_mask:0xf
	v_fmac_f32_dpp v116, -v152, v21 quad_perm:[2,2,2,2] row_mask:0xf bank_mask:0xf
	ds_read_u16_d16_hi v252, v123 offset:5440
	v_fmac_f32_dpp v117, -v153, v22 quad_perm:[2,2,2,2] row_mask:0xf bank_mask:0xf
	v_fmac_f32_dpp v118, -v152, v23 quad_perm:[3,3,3,3] row_mask:0xf bank_mask:0xf
	v_fmac_f32_dpp v119, -v153, v24 quad_perm:[3,3,3,3] row_mask:0xf bank_mask:0xf
	ds_read_b64 v[196:197], v125 offset:5712
	v_fmac_f32_dpp v116, -v154, v25 quad_perm:[0,0,0,0] row_mask:0xf bank_mask:0xf
	v_add_f32_e32 v121, v117, v116
	v_add_f32_e32 v122, v118, v119
	v_add_f32_e32 v27, v122, v121
	s_waitcnt lgkmcnt(11)
	v_mul_f32_dpp v120, v156, v4 quad_perm:[0,0,0,0] row_mask:0xf bank_mask:0xf
	v_fma_f32 v116, v208, v250, -v120
	v_mul_f32_dpp v117, -v157, v5 quad_perm:[0,0,0,0] row_mask:0xf bank_mask:0xf
	v_mul_f32_dpp v118, -v156, v6 quad_perm:[1,1,1,1] row_mask:0xf bank_mask:0xf
	ds_read_b64 v[198:199], v125 offset:5744
	v_mul_f32_dpp v119, -v157, v12 quad_perm:[1,1,1,1] row_mask:0xf bank_mask:0xf
	v_fmac_f32_dpp v116, -v156, v7 quad_perm:[2,2,2,2] row_mask:0xf bank_mask:0xf
	v_fmac_f32_dpp v117, -v157, v13 quad_perm:[2,2,2,2] row_mask:0xf bank_mask:0xf
	ds_read_b64 v[200:201], v125 offset:5776
	v_fmac_f32_dpp v118, -v156, v14 quad_perm:[3,3,3,3] row_mask:0xf bank_mask:0xf
	v_fmac_f32_dpp v119, -v157, v15 quad_perm:[3,3,3,3] row_mask:0xf bank_mask:0xf
	v_fmac_f32_dpp v116, -v158, v16 quad_perm:[0,0,0,0] row_mask:0xf bank_mask:0xf
	ds_read_b32 v211, v124 offset:84
	v_fmac_f32_dpp v117, -v159, v17 quad_perm:[0,0,0,0] row_mask:0xf bank_mask:0xf
	v_fmac_f32_dpp v118, -v158, v19 quad_perm:[1,1,1,1] row_mask:0xf bank_mask:0xf
	v_fmac_f32_dpp v119, -v159, v20 quad_perm:[1,1,1,1] row_mask:0xf bank_mask:0xf
	ds_read_u16_d16_hi v253, v123 offset:5712
	v_fmac_f32_dpp v116, -v158, v21 quad_perm:[2,2,2,2] row_mask:0xf bank_mask:0xf
	v_fmac_f32_dpp v117, -v159, v22 quad_perm:[2,2,2,2] row_mask:0xf bank_mask:0xf
	v_fmac_f32_dpp v118, -v158, v23 quad_perm:[3,3,3,3] row_mask:0xf bank_mask:0xf
	ds_read_b64 v[202:203], v125 offset:5984
	v_fmac_f32_dpp v119, -v159, v24 quad_perm:[3,3,3,3] row_mask:0xf bank_mask:0xf
	v_fmac_f32_dpp v116, -v160, v25 quad_perm:[0,0,0,0] row_mask:0xf bank_mask:0xf
	v_fmac_f32_dpp v117, -v161, v27 quad_perm:[0,0,0,0] row_mask:0xf bank_mask:0xf
	ds_read_b64 v[204:205], v125 offset:6016
	v_add_f32_e32 v121, v117, v116
	v_add_f32_e32 v122, v118, v119
	v_add_f32_e32 v28, v122, v121
	s_waitcnt lgkmcnt(12)
	v_mul_f32_dpp v120, v162, v4 quad_perm:[0,0,0,0] row_mask:0xf bank_mask:0xf
	v_fma_f32 v116, v209, v251, -v120
	v_mul_f32_dpp v117, -v163, v5 quad_perm:[0,0,0,0] row_mask:0xf bank_mask:0xf
	v_mul_f32_dpp v118, -v162, v6 quad_perm:[1,1,1,1] row_mask:0xf bank_mask:0xf
	v_mul_f32_dpp v119, -v163, v12 quad_perm:[1,1,1,1] row_mask:0xf bank_mask:0xf
	ds_read_b64 v[206:207], v125 offset:6048
	v_fmac_f32_dpp v116, -v162, v7 quad_perm:[2,2,2,2] row_mask:0xf bank_mask:0xf
	v_fmac_f32_dpp v117, -v163, v13 quad_perm:[2,2,2,2] row_mask:0xf bank_mask:0xf
	v_fmac_f32_dpp v118, -v162, v14 quad_perm:[3,3,3,3] row_mask:0xf bank_mask:0xf
	ds_read_b32 v212, v124 offset:88
	v_fmac_f32_dpp v119, -v163, v15 quad_perm:[3,3,3,3] row_mask:0xf bank_mask:0xf
	v_fmac_f32_dpp v116, -v186, v16 quad_perm:[0,0,0,0] row_mask:0xf bank_mask:0xf
	v_fmac_f32_dpp v117, -v187, v17 quad_perm:[0,0,0,0] row_mask:0xf bank_mask:0xf
	ds_read_u16_d16_hi v126, v123 offset:5984
	v_fmac_f32_dpp v118, -v186, v19 quad_perm:[1,1,1,1] row_mask:0xf bank_mask:0xf
	v_fmac_f32_dpp v119, -v187, v20 quad_perm:[1,1,1,1] row_mask:0xf bank_mask:0xf
	v_fmac_f32_dpp v116, -v186, v21 quad_perm:[2,2,2,2] row_mask:0xf bank_mask:0xf
	ds_read_b64 v[164:165], v125 offset:6256
	v_fmac_f32_dpp v117, -v187, v22 quad_perm:[2,2,2,2] row_mask:0xf bank_mask:0xf
	v_fmac_f32_dpp v118, -v186, v23 quad_perm:[3,3,3,3] row_mask:0xf bank_mask:0xf
	v_fmac_f32_dpp v119, -v187, v24 quad_perm:[3,3,3,3] row_mask:0xf bank_mask:0xf
	ds_read_b64 v[166:167], v125 offset:6288
	v_fmac_f32_dpp v116, -v188, v25 quad_perm:[0,0,0,0] row_mask:0xf bank_mask:0xf
	v_fmac_f32_dpp v117, -v189, v27 quad_perm:[0,0,0,0] row_mask:0xf bank_mask:0xf
	v_fmac_f32_dpp v118, -v188, v28 quad_perm:[1,1,1,1] row_mask:0xf bank_mask:0xf
	ds_read_b64 v[168:169], v125 offset:6320
	v_add_f32_e32 v121, v117, v116
	v_add_f32_e32 v122, v118, v119
	v_add_f32_e32 v29, v122, v121
	s_waitcnt lgkmcnt(13)
; #define GDN_LOADROW(buf, rr_, i_) do { _Pragma("unroll") for (int j4 = 0; j4 < ((i_) + 3) / 4; ++j4) buf[j4] = *(const f32x4*)(Lm + (i_) * GP_LSTR + 4 * j4); rr_ = bf2f(*(const bf16*)(xsrc + (i_) * GP_STR * 2)) * scl[i_]; } while (0)
; template <int STRIP> __device__ __forceinline__ void ph_gdn_prep_fast(const bf16* __restrict__ proj, const float* __restrict__ small, const float* __restrict__ conv_w, const float* __restrict__ a_log, const float* __restrict__ dt_bias, ...
;     ...
; #pragma unroll
;             for (int i = 0; i < 64; i += 2) {
;                 GDN_LOADROW(bB, rB, i + 1);
;                 GDN_ROW(bA, rA, i);
;                 if (i + 2 < 64) GDN_LOADROW(bA, rA, i + 2);
;                 GDN_ROW(bB, rB, i + 1);
;             }
	v_mul_f32_dpp v120, v190, v4 quad_perm:[0,0,0,0] row_mask:0xf bank_mask:0xf
	v_fma_f32 v116, v210, v252, -v120
	v_mul_f32_dpp v117, -v191, v5 quad_perm:[0,0,0,0] row_mask:0xf bank_mask:0xf
	v_mul_f32_dpp v118, -v190, v6 quad_perm:[1,1,1,1] row_mask:0xf bank_mask:0xf
	v_mul_f32_dpp v119, -v191, v12 quad_perm:[1,1,1,1] row_mask:0xf bank_mask:0xf
	ds_read_b32 v213, v124 offset:92
	v_fmac_f32_dpp v116, -v190, v7 quad_perm:[2,2,2,2] row_mask:0xf bank_mask:0xf
	v_fmac_f32_dpp v117, -v191, v13 quad_perm:[2,2,2,2] row_mask:0xf bank_mask:0xf
	v_fmac_f32_dpp v118, -v190, v14 quad_perm:[3,3,3,3] row_mask:0xf bank_mask:0xf
	ds_read_u16_d16_hi v127, v123 offset:6256
	v_fmac_f32_dpp v119, -v191, v15 quad_perm:[3,3,3,3] row_mask:0xf bank_mask:0xf
	v_fmac_f32_dpp v116, -v192, v16 quad_perm:[0,0,0,0] row_mask:0xf bank_mask:0xf
	v_fmac_f32_dpp v117, -v193, v17 quad_perm:[0,0,0,0] row_mask:0xf bank_mask:0xf
	ds_read_b64 v[170:171], v125 offset:6528
	v_fmac_f32_dpp v118, -v192, v19 quad_perm:[1,1,1,1] row_mask:0xf bank_mask:0xf
	v_fmac_f32_dpp v119, -v193, v20 quad_perm:[1,1,1,1] row_mask:0xf bank_mask:0xf
	v_fmac_f32_dpp v116, -v192, v21 quad_perm:[2,2,2,2] row_mask:0xf bank_mask:0xf
	ds_read_b64 v[132:133], v125 offset:6560
	v_fmac_f32_dpp v117, -v193, v22 quad_perm:[2,2,2,2] row_mask:0xf bank_mask:0xf
	v_fmac_f32_dpp v118, -v192, v23 quad_perm:[3,3,3,3] row_mask:0xf bank_mask:0xf
	v_fmac_f32_dpp v119, -v193, v24 quad_perm:[3,3,3,3] row_mask:0xf bank_mask:0xf
	ds_read_b64 v[134:135], v125 offset:6592
	v_fmac_f32_dpp v116, -v194, v25 quad_perm:[0,0,0,0] row_mask:0xf bank_mask:0xf
	v_fmac_f32_dpp v117, -v195, v27 quad_perm:[0,0,0,0] row_mask:0xf bank_mask:0xf
	v_fmac_f32_dpp v118, -v194, v28 quad_perm:[1,1,1,1] row_mask:0xf bank_mask:0xf
	ds_read_b32 v214, v124 offset:96
	v_fmac_f32_dpp v119, -v195, v29 quad_perm:[1,1,1,1] row_mask:0xf bank_mask:0xf
	v_add_f32_e32 v121, v117, v116
	v_add_f32_e32 v122, v118, v119
	v_add_f32_e32 v30, v122, v121
	s_waitcnt lgkmcnt(14)
	v_mul_f32_dpp v120, v196, v4 quad_perm:[0,0,0,0] row_mask:0xf bank_mask:0xf
	v_fma_f32 v116, v211, v253, -v120
	v_mul_f32_dpp v117, -v197, v5 quad_perm:[0,0,0,0] row_mask:0xf bank_mask:0xf
	v_mul_f32_dpp v118, -v196, v6 quad_perm:[1,1,1,1] row_mask:0xf bank_mask:0xf
	ds_read_u16_d16_hi v244, v123 offset:6528
	v_mul_f32_dpp v119, -v197, v12 quad_perm:[1,1,1,1] row_mask:0xf bank_mask:0xf
	v_fmac_f32_dpp v116, -v196, v7 quad_perm:[2,2,2,2] row_mask:0xf bank_mask:0xf
	v_fmac_f32_dpp v117, -v197, v13 quad_perm:[2,2,2,2] row_mask:0xf bank_mask:0xf
	ds_read_b64 v[136:137], v125 offset:6800
	v_fmac_f32_dpp v118, -v196, v14 quad_perm:[3,3,3,3] row_mask:0xf bank_mask:0xf
	v_fmac_f32_dpp v119, -v197, v15 quad_perm:[3,3,3,3] row_mask:0xf bank_mask:0xf
	v_fmac_f32_dpp v116, -v198, v16 quad_perm:[0,0,0,0] row_mask:0xf bank_mask:0xf
	ds_read_b64 v[138:139], v125 offset:6832
	v_fmac_f32_dpp v117, -v199, v17 quad_perm:[0,0,0,0] row_mask:0xf bank_mask:0xf
	v_fmac_f32_dpp v118, -v198, v19 quad_perm:[1,1,1,1] row_mask:0xf bank_mask:0xf
	v_fmac_f32_dpp v119, -v199, v20 quad_perm:[1,1,1,1] row_mask:0xf bank_mask:0xf
	ds_read_b64 v[140:141], v125 offset:6864
	v_fmac_f32_dpp v116, -v198, v21 quad_perm:[2,2,2,2] row_mask:0xf bank_mask:0xf
	v_fmac_f32_dpp v117, -v199, v22 quad_perm:[2,2,2,2] row_mask:0xf bank_mask:0xf
	v_fmac_f32_dpp v118, -v198, v23 quad_perm:[3,3,3,3] row_mask:0xf bank_mask:0xf
	ds_read_b64 v[142:143], v125 offset:6896
	v_fmac_f32_dpp v119, -v199, v24 quad_perm:[3,3,3,3] row_mask:0xf bank_mask:0xf
	v_fmac_f32_dpp v116, -v200, v25 quad_perm:[0,0,0,0] row_mask:0xf bank_mask:0xf
	v_fmac_f32_dpp v117, -v201, v27 quad_perm:[0,0,0,0] row_mask:0xf bank_mask:0xf
	ds_read_b32 v215, v124 offset:100
	v_fmac_f32_dpp v118, -v200, v28 quad_perm:[1,1,1,1] row_mask:0xf bank_mask:0xf
	v_fmac_f32_dpp v119, -v201, v29 quad_perm:[1,1,1,1] row_mask:0xf bank_mask:0xf
	v_fmac_f32_dpp v116, -v200, v30 quad_perm:[2,2,2,2] row_mask:0xf bank_mask:0xf
	ds_read_u16_d16_hi v245, v123 offset:6800
	v_add_f32_e32 v121, v117, v116
	v_add_f32_e32 v122, v118, v119
	v_add_f32_e32 v31, v122, v121
	s_waitcnt lgkmcnt(15)
	v_mul_f32_dpp v120, v202, v4 quad_perm:[0,0,0,0] row_mask:0xf bank_mask:0xf
	v_fma_f32 v116, v212, v126, -v120
	v_mul_f32_dpp v117, -v203, v5 quad_perm:[0,0,0,0] row_mask:0xf bank_mask:0xf
	v_mul_f32_dpp v118, -v202, v6 quad_perm:[1,1,1,1] row_mask:0xf bank_mask:0xf
	v_mul_f32_dpp v119, -v203, v12 quad_perm:[1,1,1,1] row_mask:0xf bank_mask:0xf
	ds_read_b64 v[144:145], v125 offset:7072
	v_fmac_f32_dpp v116, -v202, v7 quad_perm:[2,2,2,2] row_mask:0xf bank_mask:0xf
	v_fmac_f32_dpp v117, -v203, v13 quad_perm:[2,2,2,2] row_mask:0xf bank_mask:0xf
	v_fmac_f32_dpp v118, -v202, v14 quad_perm:[3,3,3,3] row_mask:0xf bank_mask:0xf
	ds_read_b64 v[146:147], v125 offset:7104
	v_fmac_f32_dpp v119, -v203, v15 quad_perm:[3,3,3,3] row_mask:0xf bank_mask:0xf
	v_fmac_f32_dpp v116, -v204, v16 quad_perm:[0,0,0,0] row_mask:0xf bank_mask:0xf
	v_fmac_f32_dpp v117, -v205, v17 quad_perm:[0,0,0,0] row_mask:0xf bank_mask:0xf
	ds_read_b64 v[148:149], v125 offset:7136
	v_fmac_f32_dpp v118, -v204, v19 quad_perm:[1,1,1,1] row_mask:0xf bank_mask:0xf
	v_fmac_f32_dpp v119, -v205, v20 quad_perm:[1,1,1,1] row_mask:0xf bank_mask:0xf
	v_fmac_f32_dpp v116, -v204, v21 quad_perm:[2,2,2,2] row_mask:0xf bank_mask:0xf
	ds_read_b64 v[150:151], v125 offset:7168
	v_fmac_f32_dpp v117, -v205, v22 quad_perm:[2,2,2,2] row_mask:0xf bank_mask:0xf
	v_fmac_f32_dpp v118, -v204, v23 quad_perm:[3,3,3,3] row_mask:0xf bank_mask:0xf
	v_fmac_f32_dpp v119, -v205, v24 quad_perm:[3,3,3,3] row_mask:0xf bank_mask:0xf
	ds_read_b32 v216, v124 offset:104
	v_fmac_f32_dpp v116, -v206, v25 quad_perm:[0,0,0,0] row_mask:0xf bank_mask:0xf
	v_fmac_f32_dpp v117, -v207, v27 quad_perm:[0,0,0,0] row_mask:0xf bank_mask:0xf
	v_fmac_f32_dpp v118, -v206, v28 quad_perm:[1,1,1,1] row_mask:0xf bank_mask:0xf
	ds_read_u16_d16_hi v246, v123 offset:7072
	v_fmac_f32_dpp v119, -v207, v29 quad_perm:[1,1,1,1] row_mask:0xf bank_mask:0xf
	v_fmac_f32_dpp v116, -v206, v30 quad_perm:[2,2,2,2] row_mask:0xf bank_mask:0xf
	v_fmac_f32_dpp v117, -v207, v31 quad_perm:[2,2,2,2] row_mask:0xf bank_mask:0xf
	ds_read_b64 v[152:153], v125 offset:7344
	v_add_f32_e32 v121, v117, v116
	v_add_f32_e32 v122, v118, v119
	v_add_f32_e32 v32, v122, v121
	s_waitcnt lgkmcnt(15)
; #define GDN_LOADROW(buf, rr_, i_) do { _Pragma("unroll") for (int j4 = 0; j4 < ((i_) + 3) / 4; ++j4) buf[j4] = *(const f32x4*)(Lm + (i_) * GP_LSTR + 4 * j4); rr_ = bf2f(*(const bf16*)(xsrc + (i_) * GP_STR * 2)) * scl[i_]; } while (0)
; template <int STRIP> __device__ __forceinline__ void ph_gdn_prep_fast(const bf16* __restrict__ proj, const float* __restrict__ small, const float* __restrict__ conv_w, const float* __restrict__ a_log, const float* __restrict__ dt_bias, ...
;     ...
; #pragma unroll
;             for (int i = 0; i < 64; i += 2) {
;                 GDN_LOADROW(bB, rB, i + 1);
;                 GDN_ROW(bA, rA, i);
;                 if (i + 2 < 64) GDN_LOADROW(bA, rA, i + 2);
;                 GDN_ROW(bB, rB, i + 1);
;             }
	v_mul_f32_dpp v120, v164, v4 quad_perm:[0,0,0,0] row_mask:0xf bank_mask:0xf
	v_fma_f32 v116, v213, v127, -v120
	v_mul_f32_dpp v117, -v165, v5 quad_perm:[0,0,0,0] row_mask:0xf bank_mask:0xf
	v_mul_f32_dpp v118, -v164, v6 quad_perm:[1,1,1,1] row_mask:0xf bank_mask:0xf
	v_mul_f32_dpp v119, -v165, v12 quad_perm:[1,1,1,1] row_mask:0xf bank_mask:0xf
	ds_read_b64 v[154:155], v125 offset:7376
	v_fmac_f32_dpp v116, -v164, v7 quad_perm:[2,2,2,2] row_mask:0xf bank_mask:0xf
	v_fmac_f32_dpp v117, -v165, v13 quad_perm:[2,2,2,2] row_mask:0xf bank_mask:0xf
	v_fmac_f32_dpp v118, -v164, v14 quad_perm:[3,3,3,3] row_mask:0xf bank_mask:0xf
	ds_read_b64 v[156:157], v125 offset:7408
	v_fmac_f32_dpp v119, -v165, v15 quad_perm:[3,3,3,3] row_mask:0xf bank_mask:0xf
	v_fmac_f32_dpp v116, -v166, v16 quad_perm:[0,0,0,0] row_mask:0xf bank_mask:0xf
	v_fmac_f32_dpp v117, -v167, v17 quad_perm:[0,0,0,0] row_mask:0xf bank_mask:0xf
	ds_read_b64 v[158:159], v125 offset:7440
	v_fmac_f32_dpp v118, -v166, v19 quad_perm:[1,1,1,1] row_mask:0xf bank_mask:0xf
	v_fmac_f32_dpp v119, -v167, v20 quad_perm:[1,1,1,1] row_mask:0xf bank_mask:0xf
	v_fmac_f32_dpp v116, -v166, v21 quad_perm:[2,2,2,2] row_mask:0xf bank_mask:0xf
	ds_read_b32 v217, v124 offset:108
	v_fmac_f32_dpp v117, -v167, v22 quad_perm:[2,2,2,2] row_mask:0xf bank_mask:0xf
	v_fmac_f32_dpp v118, -v166, v23 quad_perm:[3,3,3,3] row_mask:0xf bank_mask:0xf
	v_fmac_f32_dpp v119, -v167, v24 quad_perm:[3,3,3,3] row_mask:0xf bank_mask:0xf
	ds_read_u16_d16_hi v247, v123 offset:7344
	v_fmac_f32_dpp v116, -v168, v25 quad_perm:[0,0,0,0] row_mask:0xf bank_mask:0xf
	v_fmac_f32_dpp v117, -v169, v27 quad_perm:[0,0,0,0] row_mask:0xf bank_mask:0xf
	v_fmac_f32_dpp v118, -v168, v28 quad_perm:[1,1,1,1] row_mask:0xf bank_mask:0xf
	v_fmac_f32_dpp v119, -v169, v29 quad_perm:[1,1,1,1] row_mask:0xf bank_mask:0xf
	v_fmac_f32_dpp v116, -v168, v30 quad_perm:[2,2,2,2] row_mask:0xf bank_mask:0xf
	v_fmac_f32_dpp v117, -v169, v31 quad_perm:[2,2,2,2] row_mask:0xf bank_mask:0xf
	v_fmac_f32_dpp v118, -v168, v32 quad_perm:[3,3,3,3] row_mask:0xf bank_mask:0xf
	v_add_f32_e32 v121, v117, v116
	v_add_f32_e32 v122, v118, v119
	v_add_f32_e32 v33, v122, v121
	s_waitcnt lgkmcnt(15)
	v_mul_f32_dpp v120, v170, v4 quad_perm:[0,0,0,0] row_mask:0xf bank_mask:0xf
	v_fma_f32 v116, v214, v244, -v120
	v_mul_f32_dpp v117, -v171, v5 quad_perm:[0,0,0,0] row_mask:0xf bank_mask:0xf
	v_mul_f32_dpp v118, -v170, v6 quad_perm:[1,1,1,1] row_mask:0xf bank_mask:0xf
	ds_read_b64 v[160:161], v125 offset:7616
	v_mul_f32_dpp v119, -v171, v12 quad_perm:[1,1,1,1] row_mask:0xf bank_mask:0xf
	v_fmac_f32_dpp v116, -v170, v7 quad_perm:[2,2,2,2] row_mask:0xf bank_mask:0xf
	v_fmac_f32_dpp v117, -v171, v13 quad_perm:[2,2,2,2] row_mask:0xf bank_mask:0xf
	ds_read_b64 v[162:163], v125 offset:7648
	v_fmac_f32_dpp v118, -v170, v14 quad_perm:[3,3,3,3] row_mask:0xf bank_mask:0xf
	v_fmac_f32_dpp v119, -v171, v15 quad_perm:[3,3,3,3] row_mask:0xf bank_mask:0xf
	v_fmac_f32_dpp v116, -v132, v16 quad_perm:[0,0,0,0] row_mask:0xf bank_mask:0xf
	ds_read_b64 v[186:187], v125 offset:7680
	v_fmac_f32_dpp v117, -v133, v17 quad_perm:[0,0,0,0] row_mask:0xf bank_mask:0xf
	v_fmac_f32_dpp v118, -v132, v19 quad_perm:[1,1,1,1] row_mask:0xf bank_mask:0xf
	v_fmac_f32_dpp v119, -v133, v20 quad_perm:[1,1,1,1] row_mask:0xf bank_mask:0xf
	ds_read_b64 v[188:189], v125 offset:7712
	v_fmac_f32_dpp v116, -v132, v21 quad_perm:[2,2,2,2] row_mask:0xf bank_mask:0xf
	v_fmac_f32_dpp v117, -v133, v22 quad_perm:[2,2,2,2] row_mask:0xf bank_mask:0xf
	v_fmac_f32_dpp v118, -v132, v23 quad_perm:[3,3,3,3] row_mask:0xf bank_mask:0xf
	ds_read_b32 v218, v124 offset:112
	v_fmac_f32_dpp v119, -v133, v24 quad_perm:[3,3,3,3] row_mask:0xf bank_mask:0xf
	v_fmac_f32_dpp v116, -v134, v25 quad_perm:[0,0,0,0] row_mask:0xf bank_mask:0xf
	v_fmac_f32_dpp v117, -v135, v27 quad_perm:[0,0,0,0] row_mask:0xf bank_mask:0xf
	ds_read_u16_d16_hi v248, v123 offset:7616
	v_fmac_f32_dpp v118, -v134, v28 quad_perm:[1,1,1,1] row_mask:0xf bank_mask:0xf
	v_fmac_f32_dpp v119, -v135, v29 quad_perm:[1,1,1,1] row_mask:0xf bank_mask:0xf
	v_fmac_f32_dpp v116, -v134, v30 quad_perm:[2,2,2,2] row_mask:0xf bank_mask:0xf
	v_fmac_f32_dpp v117, -v135, v31 quad_perm:[2,2,2,2] row_mask:0xf bank_mask:0xf
	v_fmac_f32_dpp v118, -v134, v32 quad_perm:[3,3,3,3] row_mask:0xf bank_mask:0xf
	v_fmac_f32_dpp v119, -v135, v33 quad_perm:[3,3,3,3] row_mask:0xf bank_mask:0xf
	v_add_f32_e32 v121, v117, v116
	v_add_f32_e32 v122, v118, v119
	v_add_f32_e32 v34, v122, v121
	s_waitcnt lgkmcnt(15)
; #define GDN_LOADROW(buf, rr_, i_) do { _Pragma("unroll") for (int j4 = 0; j4 < ((i_) + 3) / 4; ++j4) buf[j4] = *(const f32x4*)(Lm + (i_) * GP_LSTR + 4 * j4); rr_ = bf2f(*(const bf16*)(xsrc + (i_) * GP_STR * 2)) * scl[i_]; } while (0)
; template <int STRIP> __device__ __forceinline__ void ph_gdn_prep_fast(const bf16* __restrict__ proj, const float* __restrict__ small, const float* __restrict__ conv_w, const float* __restrict__ a_log, const float* __restrict__ dt_bias, ...
;     ...
; #pragma unroll
;             for (int i = 0; i < 64; i += 2) {
;                 GDN_LOADROW(bB, rB, i + 1);
;                 GDN_ROW(bA, rA, i);
;                 if (i + 2 < 64) GDN_LOADROW(bA, rA, i + 2);
;                 GDN_ROW(bB, rB, i + 1);
;             }
	v_mul_f32_dpp v120, v136, v4 quad_perm:[0,0,0,0] row_mask:0xf bank_mask:0xf
	v_fma_f32 v116, v215, v245, -v120
	v_mul_f32_dpp v117, -v137, v5 quad_perm:[0,0,0,0] row_mask:0xf bank_mask:0xf
	v_mul_f32_dpp v118, -v136, v6 quad_perm:[1,1,1,1] row_mask:0xf bank_mask:0xf
	v_mul_f32_dpp v119, -v137, v12 quad_perm:[1,1,1,1] row_mask:0xf bank_mask:0xf
	ds_read_b64 v[190:191], v125 offset:7888
	v_fmac_f32_dpp v116, -v136, v7 quad_perm:[2,2,2,2] row_mask:0xf bank_mask:0xf
	v_fmac_f32_dpp v117, -v137, v13 quad_perm:[2,2,2,2] row_mask:0xf bank_mask:0xf
	v_fmac_f32_dpp v118, -v136, v14 quad_perm:[3,3,3,3] row_mask:0xf bank_mask:0xf
	ds_read_b64 v[192:193], v125 offset:7920
	v_fmac_f32_dpp v119, -v137, v15 quad_perm:[3,3,3,3] row_mask:0xf bank_mask:0xf
	v_fmac_f32_dpp v116, -v138, v16 quad_perm:[0,0,0,0] row_mask:0xf bank_mask:0xf
	v_fmac_f32_dpp v117, -v139, v17 quad_perm:[0,0,0,0] row_mask:0xf bank_mask:0xf
	ds_read_b64 v[194:195], v125 offset:7952
	v_fmac_f32_dpp v118, -v138, v19 quad_perm:[1,1,1,1] row_mask:0xf bank_mask:0xf
	v_fmac_f32_dpp v119, -v139, v20 quad_perm:[1,1,1,1] row_mask:0xf bank_mask:0xf
	v_fmac_f32_dpp v116, -v138, v21 quad_perm:[2,2,2,2] row_mask:0xf bank_mask:0xf
	ds_read_b64 v[196:197], v125 offset:7984
	v_fmac_f32_dpp v117, -v139, v22 quad_perm:[2,2,2,2] row_mask:0xf bank_mask:0xf
	v_fmac_f32_dpp v118, -v138, v23 quad_perm:[3,3,3,3] row_mask:0xf bank_mask:0xf
	v_fmac_f32_dpp v119, -v139, v24 quad_perm:[3,3,3,3] row_mask:0xf bank_mask:0xf
	ds_read_b32 v219, v124 offset:116
	v_fmac_f32_dpp v116, -v140, v25 quad_perm:[0,0,0,0] row_mask:0xf bank_mask:0xf
	v_fmac_f32_dpp v117, -v141, v27 quad_perm:[0,0,0,0] row_mask:0xf bank_mask:0xf
	v_fmac_f32_dpp v118, -v140, v28 quad_perm:[1,1,1,1] row_mask:0xf bank_mask:0xf
	ds_read_u16_d16_hi v249, v123 offset:7888
	v_fmac_f32_dpp v119, -v141, v29 quad_perm:[1,1,1,1] row_mask:0xf bank_mask:0xf
	v_fmac_f32_dpp v116, -v140, v30 quad_perm:[2,2,2,2] row_mask:0xf bank_mask:0xf
	v_fmac_f32_dpp v117, -v141, v31 quad_perm:[2,2,2,2] row_mask:0xf bank_mask:0xf
	v_fmac_f32_dpp v118, -v140, v32 quad_perm:[3,3,3,3] row_mask:0xf bank_mask:0xf
	v_fmac_f32_dpp v119, -v141, v33 quad_perm:[3,3,3,3] row_mask:0xf bank_mask:0xf
	v_fmac_f32_dpp v116, -v142, v34 quad_perm:[0,0,0,0] row_mask:0xf bank_mask:0xf
	v_add_f32_e32 v121, v117, v116
	v_add_f32_e32 v122, v118, v119
	v_add_f32_e32 v35, v122, v121
	s_waitcnt lgkmcnt(15)
	v_mul_f32_dpp v120, v144, v4 quad_perm:[0,0,0,0] row_mask:0xf bank_mask:0xf
	v_fma_f32 v116, v216, v246, -v120
	v_mul_f32_dpp v117, -v145, v5 quad_perm:[0,0,0,0] row_mask:0xf bank_mask:0xf
	v_mul_f32_dpp v118, -v144, v6 quad_perm:[1,1,1,1] row_mask:0xf bank_mask:0xf
	v_mul_f32_dpp v119, -v145, v12 quad_perm:[1,1,1,1] row_mask:0xf bank_mask:0xf
	ds_read_b64 v[198:199], v125 offset:8160
	v_fmac_f32_dpp v116, -v144, v7 quad_perm:[2,2,2,2] row_mask:0xf bank_mask:0xf
	v_fmac_f32_dpp v117, -v145, v13 quad_perm:[2,2,2,2] row_mask:0xf bank_mask:0xf
	v_fmac_f32_dpp v118, -v144, v14 quad_perm:[3,3,3,3] row_mask:0xf bank_mask:0xf
	ds_read_b64 v[200:201], v125 offset:8192
	v_fmac_f32_dpp v119, -v145, v15 quad_perm:[3,3,3,3] row_mask:0xf bank_mask:0xf
	v_fmac_f32_dpp v116, -v146, v16 quad_perm:[0,0,0,0] row_mask:0xf bank_mask:0xf
	v_fmac_f32_dpp v117, -v147, v17 quad_perm:[0,0,0,0] row_mask:0xf bank_mask:0xf
	ds_read_b64 v[202:203], v125 offset:8224
	v_fmac_f32_dpp v118, -v146, v19 quad_perm:[1,1,1,1] row_mask:0xf bank_mask:0xf
	v_fmac_f32_dpp v119, -v147, v20 quad_perm:[1,1,1,1] row_mask:0xf bank_mask:0xf
	v_fmac_f32_dpp v116, -v146, v21 quad_perm:[2,2,2,2] row_mask:0xf bank_mask:0xf
	ds_read_b64 v[204:205], v125 offset:8256
	v_fmac_f32_dpp v117, -v147, v22 quad_perm:[2,2,2,2] row_mask:0xf bank_mask:0xf
	v_fmac_f32_dpp v118, -v146, v23 quad_perm:[3,3,3,3] row_mask:0xf bank_mask:0xf
	v_fmac_f32_dpp v119, -v147, v24 quad_perm:[3,3,3,3] row_mask:0xf bank_mask:0xf
	ds_read_b32 v220, v124 offset:120
	v_fmac_f32_dpp v116, -v148, v25 quad_perm:[0,0,0,0] row_mask:0xf bank_mask:0xf
	v_fmac_f32_dpp v117, -v149, v27 quad_perm:[0,0,0,0] row_mask:0xf bank_mask:0xf
	v_fmac_f32_dpp v118, -v148, v28 quad_perm:[1,1,1,1] row_mask:0xf bank_mask:0xf
	ds_read_u16_d16_hi v250, v123 offset:8160
	v_fmac_f32_dpp v119, -v149, v29 quad_perm:[1,1,1,1] row_mask:0xf bank_mask:0xf
	v_fmac_f32_dpp v116, -v148, v30 quad_perm:[2,2,2,2] row_mask:0xf bank_mask:0xf
	v_fmac_f32_dpp v117, -v149, v31 quad_perm:[2,2,2,2] row_mask:0xf bank_mask:0xf
	v_fmac_f32_dpp v118, -v148, v32 quad_perm:[3,3,3,3] row_mask:0xf bank_mask:0xf
	v_fmac_f32_dpp v119, -v149, v33 quad_perm:[3,3,3,3] row_mask:0xf bank_mask:0xf
	v_fmac_f32_dpp v116, -v150, v34 quad_perm:[0,0,0,0] row_mask:0xf bank_mask:0xf
	v_fmac_f32_dpp v117, -v151, v35 quad_perm:[0,0,0,0] row_mask:0xf bank_mask:0xf
	v_add_f32_e32 v121, v117, v116
	v_add_f32_e32 v122, v118, v119
	v_add_f32_e32 v36, v122, v121
	s_waitcnt lgkmcnt(15)
; #define GDN_LOADROW(buf, rr_, i_) do { _Pragma("unroll") for (int j4 = 0; j4 < ((i_) + 3) / 4; ++j4) buf[j4] = *(const f32x4*)(Lm + (i_) * GP_LSTR + 4 * j4); rr_ = bf2f(*(const bf16*)(xsrc + (i_) * GP_STR * 2)) * scl[i_]; } while (0)
; template <int STRIP> __device__ __forceinline__ void ph_gdn_prep_fast(const bf16* __restrict__ proj, const float* __restrict__ small, const float* __restrict__ conv_w, const float* __restrict__ a_log, const float* __restrict__ dt_bias, ...
;     ...
; #pragma unroll
;             for (int i = 0; i < 64; i += 2) {
;                 GDN_LOADROW(bB, rB, i + 1);
;                 GDN_ROW(bA, rA, i);
;                 if (i + 2 < 64) GDN_LOADROW(bA, rA, i + 2);
;                 GDN_ROW(bB, rB, i + 1);
;             }
	v_mul_f32_dpp v120, v152, v4 quad_perm:[0,0,0,0] row_mask:0xf bank_mask:0xf
	v_fma_f32 v116, v217, v247, -v120
	v_mul_f32_dpp v117, -v153, v5 quad_perm:[0,0,0,0] row_mask:0xf bank_mask:0xf
	v_mul_f32_dpp v118, -v152, v6 quad_perm:[1,1,1,1] row_mask:0xf bank_mask:0xf
	ds_read_b64 v[206:207], v125 offset:8432
	v_mul_f32_dpp v119, -v153, v12 quad_perm:[1,1,1,1] row_mask:0xf bank_mask:0xf
	v_fmac_f32_dpp v116, -v152, v7 quad_perm:[2,2,2,2] row_mask:0xf bank_mask:0xf
	v_fmac_f32_dpp v117, -v153, v13 quad_perm:[2,2,2,2] row_mask:0xf bank_mask:0xf
	ds_read_b64 v[164:165], v125 offset:8464
	v_fmac_f32_dpp v118, -v152, v14 quad_perm:[3,3,3,3] row_mask:0xf bank_mask:0xf
	v_fmac_f32_dpp v119, -v153, v15 quad_perm:[3,3,3,3] row_mask:0xf bank_mask:0xf
	v_fmac_f32_dpp v116, -v154, v16 quad_perm:[0,0,0,0] row_mask:0xf bank_mask:0xf
	ds_read_b64 v[166:167], v125 offset:8496
	v_fmac_f32_dpp v117, -v155, v17 quad_perm:[0,0,0,0] row_mask:0xf bank_mask:0xf
	v_fmac_f32_dpp v118, -v154, v19 quad_perm:[1,1,1,1] row_mask:0xf bank_mask:0xf
	v_fmac_f32_dpp v119, -v155, v20 quad_perm:[1,1,1,1] row_mask:0xf bank_mask:0xf
	ds_read_b64 v[168:169], v125 offset:8528
	v_fmac_f32_dpp v116, -v154, v21 quad_perm:[2,2,2,2] row_mask:0xf bank_mask:0xf
	v_fmac_f32_dpp v117, -v155, v22 quad_perm:[2,2,2,2] row_mask:0xf bank_mask:0xf
	v_fmac_f32_dpp v118, -v154, v23 quad_perm:[3,3,3,3] row_mask:0xf bank_mask:0xf
	ds_read_b32 v221, v124 offset:124
	v_fmac_f32_dpp v119, -v155, v24 quad_perm:[3,3,3,3] row_mask:0xf bank_mask:0xf
	v_fmac_f32_dpp v116, -v156, v25 quad_perm:[0,0,0,0] row_mask:0xf bank_mask:0xf
	v_fmac_f32_dpp v117, -v157, v27 quad_perm:[0,0,0,0] row_mask:0xf bank_mask:0xf
	ds_read_u16_d16_hi v251, v123 offset:8432
	v_fmac_f32_dpp v118, -v156, v28 quad_perm:[1,1,1,1] row_mask:0xf bank_mask:0xf
	v_fmac_f32_dpp v119, -v157, v29 quad_perm:[1,1,1,1] row_mask:0xf bank_mask:0xf
	v_fmac_f32_dpp v116, -v156, v30 quad_perm:[2,2,2,2] row_mask:0xf bank_mask:0xf
	v_fmac_f32_dpp v117, -v157, v31 quad_perm:[2,2,2,2] row_mask:0xf bank_mask:0xf
	v_fmac_f32_dpp v118, -v156, v32 quad_perm:[3,3,3,3] row_mask:0xf bank_mask:0xf
	v_fmac_f32_dpp v119, -v157, v33 quad_perm:[3,3,3,3] row_mask:0xf bank_mask:0xf
	v_fmac_f32_dpp v116, -v158, v34 quad_perm:[0,0,0,0] row_mask:0xf bank_mask:0xf
	v_fmac_f32_dpp v117, -v159, v35 quad_perm:[0,0,0,0] row_mask:0xf bank_mask:0xf
	v_fmac_f32_dpp v118, -v158, v36 quad_perm:[1,1,1,1] row_mask:0xf bank_mask:0xf
	v_add_f32_e32 v121, v117, v116
	v_add_f32_e32 v122, v118, v119
	v_add_f32_e32 v37, v122, v121
	s_waitcnt lgkmcnt(15)
	v_mul_f32_dpp v120, v160, v4 quad_perm:[0,0,0,0] row_mask:0xf bank_mask:0xf
	v_fma_f32 v116, v218, v248, -v120
	v_mul_f32_dpp v117, -v161, v5 quad_perm:[0,0,0,0] row_mask:0xf bank_mask:0xf
	v_mul_f32_dpp v118, -v160, v6 quad_perm:[1,1,1,1] row_mask:0xf bank_mask:0xf
	v_mul_f32_dpp v119, -v161, v12 quad_perm:[1,1,1,1] row_mask:0xf bank_mask:0xf
	v_fmac_f32_dpp v116, -v160, v7 quad_perm:[2,2,2,2] row_mask:0xf bank_mask:0xf
	v_fmac_f32_dpp v117, -v161, v13 quad_perm:[2,2,2,2] row_mask:0xf bank_mask:0xf
	v_fmac_f32_dpp v118, -v160, v14 quad_perm:[3,3,3,3] row_mask:0xf bank_mask:0xf
	v_fmac_f32_dpp v119, -v161, v15 quad_perm:[3,3,3,3] row_mask:0xf bank_mask:0xf
	v_fmac_f32_dpp v116, -v162, v16 quad_perm:[0,0,0,0] row_mask:0xf bank_mask:0xf
	v_fmac_f32_dpp v117, -v163, v17 quad_perm:[0,0,0,0] row_mask:0xf bank_mask:0xf
	v_fmac_f32_dpp v118, -v162, v19 quad_perm:[1,1,1,1] row_mask:0xf bank_mask:0xf
	v_fmac_f32_dpp v119, -v163, v20 quad_perm:[1,1,1,1] row_mask:0xf bank_mask:0xf
	v_fmac_f32_dpp v116, -v162, v21 quad_perm:[2,2,2,2] row_mask:0xf bank_mask:0xf
	v_fmac_f32_dpp v117, -v163, v22 quad_perm:[2,2,2,2] row_mask:0xf bank_mask:0xf
	v_fmac_f32_dpp v118, -v162, v23 quad_perm:[3,3,3,3] row_mask:0xf bank_mask:0xf
	v_fmac_f32_dpp v119, -v163, v24 quad_perm:[3,3,3,3] row_mask:0xf bank_mask:0xf
	v_fmac_f32_dpp v116, -v186, v25 quad_perm:[0,0,0,0] row_mask:0xf bank_mask:0xf
	v_fmac_f32_dpp v117, -v187, v27 quad_perm:[0,0,0,0] row_mask:0xf bank_mask:0xf
	v_fmac_f32_dpp v118, -v186, v28 quad_perm:[1,1,1,1] row_mask:0xf bank_mask:0xf
	v_fmac_f32_dpp v119, -v187, v29 quad_perm:[1,1,1,1] row_mask:0xf bank_mask:0xf
	v_fmac_f32_dpp v116, -v186, v30 quad_perm:[2,2,2,2] row_mask:0xf bank_mask:0xf
	v_fmac_f32_dpp v117, -v187, v31 quad_perm:[2,2,2,2] row_mask:0xf bank_mask:0xf
	v_fmac_f32_dpp v118, -v186, v32 quad_perm:[3,3,3,3] row_mask:0xf bank_mask:0xf
	v_fmac_f32_dpp v119, -v187, v33 quad_perm:[3,3,3,3] row_mask:0xf bank_mask:0xf
	v_fmac_f32_dpp v116, -v188, v34 quad_perm:[0,0,0,0] row_mask:0xf bank_mask:0xf
	v_fmac_f32_dpp v117, -v189, v35 quad_perm:[0,0,0,0] row_mask:0xf bank_mask:0xf
	v_fmac_f32_dpp v118, -v188, v36 quad_perm:[1,1,1,1] row_mask:0xf bank_mask:0xf
	v_fmac_f32_dpp v119, -v189, v37 quad_perm:[1,1,1,1] row_mask:0xf bank_mask:0xf
	v_add_f32_e32 v121, v117, v116
	v_add_f32_e32 v122, v118, v119
	v_add_f32_e32 v38, v122, v121
	s_waitcnt lgkmcnt(12)
; #define GDN_LOADROW(buf, rr_, i_) do { _Pragma("unroll") for (int j4 = 0; j4 < ((i_) + 3) / 4; ++j4) buf[j4] = *(const f32x4*)(Lm + (i_) * GP_LSTR + 4 * j4); rr_ = bf2f(*(const bf16*)(xsrc + (i_) * GP_STR * 2)) * scl[i_]; } while (0)
; template <int STRIP> __device__ __forceinline__ void ph_gdn_prep_fast(const bf16* __restrict__ proj, const float* __restrict__ small, const float* __restrict__ conv_w, const float* __restrict__ a_log, const float* __restrict__ dt_bias, ...
;     ...
; #pragma unroll
;             for (int i = 0; i < 64; i += 2) {
;                 GDN_LOADROW(bB, rB, i + 1);
;                 GDN_ROW(bA, rA, i);
;                 if (i + 2 < 64) GDN_LOADROW(bA, rA, i + 2);
;                 GDN_ROW(bB, rB, i + 1);
;             }
	v_mul_f32_dpp v120, v190, v4 quad_perm:[0,0,0,0] row_mask:0xf bank_mask:0xf
	v_fma_f32 v116, v219, v249, -v120
	v_mul_f32_dpp v117, -v191, v5 quad_perm:[0,0,0,0] row_mask:0xf bank_mask:0xf
	v_mul_f32_dpp v118, -v190, v6 quad_perm:[1,1,1,1] row_mask:0xf bank_mask:0xf
	v_mul_f32_dpp v119, -v191, v12 quad_perm:[1,1,1,1] row_mask:0xf bank_mask:0xf
	v_fmac_f32_dpp v116, -v190, v7 quad_perm:[2,2,2,2] row_mask:0xf bank_mask:0xf
	v_fmac_f32_dpp v117, -v191, v13 quad_perm:[2,2,2,2] row_mask:0xf bank_mask:0xf
	v_fmac_f32_dpp v118, -v190, v14 quad_perm:[3,3,3,3] row_mask:0xf bank_mask:0xf
	v_fmac_f32_dpp v119, -v191, v15 quad_perm:[3,3,3,3] row_mask:0xf bank_mask:0xf
	v_fmac_f32_dpp v116, -v192, v16 quad_perm:[0,0,0,0] row_mask:0xf bank_mask:0xf
	v_fmac_f32_dpp v117, -v193, v17 quad_perm:[0,0,0,0] row_mask:0xf bank_mask:0xf
	v_fmac_f32_dpp v118, -v192, v19 quad_perm:[1,1,1,1] row_mask:0xf bank_mask:0xf
	v_fmac_f32_dpp v119, -v193, v20 quad_perm:[1,1,1,1] row_mask:0xf bank_mask:0xf
	v_fmac_f32_dpp v116, -v192, v21 quad_perm:[2,2,2,2] row_mask:0xf bank_mask:0xf
	v_fmac_f32_dpp v117, -v193, v22 quad_perm:[2,2,2,2] row_mask:0xf bank_mask:0xf
	v_fmac_f32_dpp v118, -v192, v23 quad_perm:[3,3,3,3] row_mask:0xf bank_mask:0xf
	v_fmac_f32_dpp v119, -v193, v24 quad_perm:[3,3,3,3] row_mask:0xf bank_mask:0xf
	v_fmac_f32_dpp v116, -v194, v25 quad_perm:[0,0,0,0] row_mask:0xf bank_mask:0xf
	v_fmac_f32_dpp v117, -v195, v27 quad_perm:[0,0,0,0] row_mask:0xf bank_mask:0xf
	v_fmac_f32_dpp v118, -v194, v28 quad_perm:[1,1,1,1] row_mask:0xf bank_mask:0xf
	v_fmac_f32_dpp v119, -v195, v29 quad_perm:[1,1,1,1] row_mask:0xf bank_mask:0xf
	v_fmac_f32_dpp v116, -v194, v30 quad_perm:[2,2,2,2] row_mask:0xf bank_mask:0xf
	v_fmac_f32_dpp v117, -v195, v31 quad_perm:[2,2,2,2] row_mask:0xf bank_mask:0xf
	v_fmac_f32_dpp v118, -v194, v32 quad_perm:[3,3,3,3] row_mask:0xf bank_mask:0xf
	v_fmac_f32_dpp v119, -v195, v33 quad_perm:[3,3,3,3] row_mask:0xf bank_mask:0xf
	v_fmac_f32_dpp v116, -v196, v34 quad_perm:[0,0,0,0] row_mask:0xf bank_mask:0xf
	v_fmac_f32_dpp v117, -v197, v35 quad_perm:[0,0,0,0] row_mask:0xf bank_mask:0xf
	v_fmac_f32_dpp v118, -v196, v36 quad_perm:[1,1,1,1] row_mask:0xf bank_mask:0xf
	v_fmac_f32_dpp v119, -v197, v37 quad_perm:[1,1,1,1] row_mask:0xf bank_mask:0xf
	v_fmac_f32_dpp v116, -v196, v38 quad_perm:[2,2,2,2] row_mask:0xf bank_mask:0xf
	v_add_f32_e32 v121, v117, v116
	v_add_f32_e32 v122, v118, v119
	v_add_f32_e32 v39, v122, v121
	s_waitcnt lgkmcnt(6)
	v_mul_f32_dpp v120, v198, v4 quad_perm:[0,0,0,0] row_mask:0xf bank_mask:0xf
	v_fma_f32 v116, v220, v250, -v120
	v_mul_f32_dpp v117, -v199, v5 quad_perm:[0,0,0,0] row_mask:0xf bank_mask:0xf
	v_mul_f32_dpp v118, -v198, v6 quad_perm:[1,1,1,1] row_mask:0xf bank_mask:0xf
	v_mul_f32_dpp v119, -v199, v12 quad_perm:[1,1,1,1] row_mask:0xf bank_mask:0xf
	v_fmac_f32_dpp v116, -v198, v7 quad_perm:[2,2,2,2] row_mask:0xf bank_mask:0xf
	v_fmac_f32_dpp v117, -v199, v13 quad_perm:[2,2,2,2] row_mask:0xf bank_mask:0xf
	v_fmac_f32_dpp v118, -v198, v14 quad_perm:[3,3,3,3] row_mask:0xf bank_mask:0xf
	v_fmac_f32_dpp v119, -v199, v15 quad_perm:[3,3,3,3] row_mask:0xf bank_mask:0xf
	v_fmac_f32_dpp v116, -v200, v16 quad_perm:[0,0,0,0] row_mask:0xf bank_mask:0xf
	v_fmac_f32_dpp v117, -v201, v17 quad_perm:[0,0,0,0] row_mask:0xf bank_mask:0xf
	v_fmac_f32_dpp v118, -v200, v19 quad_perm:[1,1,1,1] row_mask:0xf bank_mask:0xf
	v_fmac_f32_dpp v119, -v201, v20 quad_perm:[1,1,1,1] row_mask:0xf bank_mask:0xf
	v_fmac_f32_dpp v116, -v200, v21 quad_perm:[2,2,2,2] row_mask:0xf bank_mask:0xf
	v_fmac_f32_dpp v117, -v201, v22 quad_perm:[2,2,2,2] row_mask:0xf bank_mask:0xf
	v_fmac_f32_dpp v118, -v200, v23 quad_perm:[3,3,3,3] row_mask:0xf bank_mask:0xf
	v_fmac_f32_dpp v119, -v201, v24 quad_perm:[3,3,3,3] row_mask:0xf bank_mask:0xf
	v_fmac_f32_dpp v116, -v202, v25 quad_perm:[0,0,0,0] row_mask:0xf bank_mask:0xf
	v_fmac_f32_dpp v117, -v203, v27 quad_perm:[0,0,0,0] row_mask:0xf bank_mask:0xf
	v_fmac_f32_dpp v118, -v202, v28 quad_perm:[1,1,1,1] row_mask:0xf bank_mask:0xf
	v_fmac_f32_dpp v119, -v203, v29 quad_perm:[1,1,1,1] row_mask:0xf bank_mask:0xf
	v_fmac_f32_dpp v116, -v202, v30 quad_perm:[2,2,2,2] row_mask:0xf bank_mask:0xf
	v_fmac_f32_dpp v117, -v203, v31 quad_perm:[2,2,2,2] row_mask:0xf bank_mask:0xf
	v_fmac_f32_dpp v118, -v202, v32 quad_perm:[3,3,3,3] row_mask:0xf bank_mask:0xf
	v_fmac_f32_dpp v119, -v203, v33 quad_perm:[3,3,3,3] row_mask:0xf bank_mask:0xf
	v_fmac_f32_dpp v116, -v204, v34 quad_perm:[0,0,0,0] row_mask:0xf bank_mask:0xf
	v_fmac_f32_dpp v117, -v205, v35 quad_perm:[0,0,0,0] row_mask:0xf bank_mask:0xf
	v_fmac_f32_dpp v118, -v204, v36 quad_perm:[1,1,1,1] row_mask:0xf bank_mask:0xf
	v_fmac_f32_dpp v119, -v205, v37 quad_perm:[1,1,1,1] row_mask:0xf bank_mask:0xf
	v_fmac_f32_dpp v116, -v204, v38 quad_perm:[2,2,2,2] row_mask:0xf bank_mask:0xf
	v_fmac_f32_dpp v117, -v205, v39 quad_perm:[2,2,2,2] row_mask:0xf bank_mask:0xf
	v_add_f32_e32 v121, v117, v116
	v_add_f32_e32 v122, v118, v119
	v_add_f32_e32 v40, v122, v121
	s_waitcnt lgkmcnt(0)
; #define GDN_LOADROW(buf, rr_, i_) do { _Pragma("unroll") for (int j4 = 0; j4 < ((i_) + 3) / 4; ++j4) buf[j4] = *(const f32x4*)(Lm + (i_) * GP_LSTR + 4 * j4); rr_ = bf2f(*(const bf16*)(xsrc + (i_) * GP_STR * 2)) * scl[i_]; } while (0)
; template <int STRIP> __device__ __forceinline__ void ph_gdn_prep_fast(const bf16* __restrict__ proj, const float* __restrict__ small, const float* __restrict__ conv_w, const float* __restrict__ a_log, const float* __restrict__ dt_bias, ...
;     ...
; #pragma unroll
;             for (int i = 0; i < 64; i += 2) {
;                 GDN_LOADROW(bB, rB, i + 1);
;                 GDN_ROW(bA, rA, i);
;                 if (i + 2 < 64) GDN_LOADROW(bA, rA, i + 2);
;                 GDN_ROW(bB, rB, i + 1);
;             }
	v_mul_f32_dpp v120, v206, v4 quad_perm:[0,0,0,0] row_mask:0xf bank_mask:0xf
	v_fma_f32 v116, v221, v251, -v120
	v_mul_f32_dpp v117, -v207, v5 quad_perm:[0,0,0,0] row_mask:0xf bank_mask:0xf
	v_mul_f32_dpp v118, -v206, v6 quad_perm:[1,1,1,1] row_mask:0xf bank_mask:0xf
	v_mul_f32_dpp v119, -v207, v12 quad_perm:[1,1,1,1] row_mask:0xf bank_mask:0xf
	v_fmac_f32_dpp v116, -v206, v7 quad_perm:[2,2,2,2] row_mask:0xf bank_mask:0xf
	v_fmac_f32_dpp v117, -v207, v13 quad_perm:[2,2,2,2] row_mask:0xf bank_mask:0xf
	v_fmac_f32_dpp v118, -v206, v14 quad_perm:[3,3,3,3] row_mask:0xf bank_mask:0xf
	v_fmac_f32_dpp v119, -v207, v15 quad_perm:[3,3,3,3] row_mask:0xf bank_mask:0xf
	v_fmac_f32_dpp v116, -v164, v16 quad_perm:[0,0,0,0] row_mask:0xf bank_mask:0xf
	v_fmac_f32_dpp v117, -v165, v17 quad_perm:[0,0,0,0] row_mask:0xf bank_mask:0xf
	v_fmac_f32_dpp v118, -v164, v19 quad_perm:[1,1,1,1] row_mask:0xf bank_mask:0xf
	v_fmac_f32_dpp v119, -v165, v20 quad_perm:[1,1,1,1] row_mask:0xf bank_mask:0xf
	v_fmac_f32_dpp v116, -v164, v21 quad_perm:[2,2,2,2] row_mask:0xf bank_mask:0xf
	v_fmac_f32_dpp v117, -v165, v22 quad_perm:[2,2,2,2] row_mask:0xf bank_mask:0xf
	v_fmac_f32_dpp v118, -v164, v23 quad_perm:[3,3,3,3] row_mask:0xf bank_mask:0xf
	v_fmac_f32_dpp v119, -v165, v24 quad_perm:[3,3,3,3] row_mask:0xf bank_mask:0xf
	v_fmac_f32_dpp v116, -v166, v25 quad_perm:[0,0,0,0] row_mask:0xf bank_mask:0xf
	v_fmac_f32_dpp v117, -v167, v27 quad_perm:[0,0,0,0] row_mask:0xf bank_mask:0xf
	v_fmac_f32_dpp v118, -v166, v28 quad_perm:[1,1,1,1] row_mask:0xf bank_mask:0xf
	v_fmac_f32_dpp v119, -v167, v29 quad_perm:[1,1,1,1] row_mask:0xf bank_mask:0xf
	v_fmac_f32_dpp v116, -v166, v30 quad_perm:[2,2,2,2] row_mask:0xf bank_mask:0xf
	v_fmac_f32_dpp v117, -v167, v31 quad_perm:[2,2,2,2] row_mask:0xf bank_mask:0xf
	v_fmac_f32_dpp v118, -v166, v32 quad_perm:[3,3,3,3] row_mask:0xf bank_mask:0xf
	v_fmac_f32_dpp v119, -v167, v33 quad_perm:[3,3,3,3] row_mask:0xf bank_mask:0xf
	v_fmac_f32_dpp v116, -v168, v34 quad_perm:[0,0,0,0] row_mask:0xf bank_mask:0xf
	v_fmac_f32_dpp v117, -v169, v35 quad_perm:[0,0,0,0] row_mask:0xf bank_mask:0xf
	v_fmac_f32_dpp v118, -v168, v36 quad_perm:[1,1,1,1] row_mask:0xf bank_mask:0xf
	v_fmac_f32_dpp v119, -v169, v37 quad_perm:[1,1,1,1] row_mask:0xf bank_mask:0xf
	v_fmac_f32_dpp v116, -v168, v38 quad_perm:[2,2,2,2] row_mask:0xf bank_mask:0xf
	v_fmac_f32_dpp v117, -v169, v39 quad_perm:[2,2,2,2] row_mask:0xf bank_mask:0xf
	v_fmac_f32_dpp v118, -v168, v40 quad_perm:[3,3,3,3] row_mask:0xf bank_mask:0xf
	v_add_f32_e32 v121, v117, v116
	v_add_f32_e32 v122, v118, v119
	v_add_f32_e32 v41, v122, v121
	v_permlane32_swap_b32_e32 v4, v5
	v_permlane32_swap_b32_e32 v6, v12
	v_permlane32_swap_b32_e32 v7, v13
	v_permlane32_swap_b32_e32 v14, v15
	v_permlane32_swap_b32_e32 v16, v17
	v_permlane32_swap_b32_e32 v19, v20
	v_permlane32_swap_b32_e32 v21, v22
	v_permlane32_swap_b32_e32 v23, v24
	v_permlane32_swap_b32_e32 v25, v27
	v_permlane32_swap_b32_e32 v28, v29
	v_permlane32_swap_b32_e32 v30, v31
	v_permlane32_swap_b32_e32 v32, v33
	v_permlane32_swap_b32_e32 v34, v35
	v_permlane32_swap_b32_e32 v36, v37
	v_permlane32_swap_b32_e32 v38, v39
	v_permlane32_swap_b32_e32 v40, v41
	v_mfma_f32_32x32x2_f32 v[132:147], v172, v4, 0
	ds_read_b32 v181, v124 offset:128
	v_mfma_f32_32x32x2_f32 v[148:163], v172, v5, 0
	ds_read_u16_d16_hi v252, v123 offset:8704
	v_mfma_f32_32x32x2_f32 v[132:147], v173, v6, v[132:147]
	ds_read_b64 v[170:171], v125 offset:9104
	v_mfma_f32_32x32x2_f32 v[148:163], v173, v12, v[148:163]
	ds_read_b32 v182, v124 offset:132
	v_permlane32_swap_b32_e32 v4, v5
	v_mfma_f32_32x32x2_f32 v[132:147], v174, v7, v[132:147]
	ds_read_u16_d16_hi v253, v123 offset:8976
	v_mfma_f32_32x32x2_f32 v[148:163], v174, v13, v[148:163]
	ds_read_b64 v[186:187], v125 offset:9376
	v_permlane32_swap_b32_e32 v6, v12
	v_mfma_f32_32x32x2_f32 v[132:147], v175, v14, v[132:147]
	ds_read_b32 v183, v124 offset:136
	v_mfma_f32_32x32x2_f32 v[148:163], v175, v15, v[148:163]
	ds_read_u16_d16_hi v126, v123 offset:9248
	v_permlane32_swap_b32_e32 v7, v13
	v_mfma_f32_32x32x2_f32 v[132:147], v176, v16, v[132:147]
	ds_read_b64 v[188:189], v125 offset:9648
	v_mfma_f32_32x32x2_f32 v[148:163], v176, v17, v[148:163]
	ds_read_b32 v185, v124 offset:140
	v_permlane32_swap_b32_e32 v14, v15
	v_mfma_f32_32x32x2_f32 v[132:147], v177, v19, v[132:147]
	ds_read_u16_d16_hi v127, v123 offset:9520
	v_mfma_f32_32x32x2_f32 v[148:163], v177, v20, v[148:163]
	ds_read_b64 v[190:191], v125 offset:9920
	v_permlane32_swap_b32_e32 v16, v17
	v_mfma_f32_32x32x2_f32 v[132:147], v178, v21, v[132:147]
	ds_read_b32 v208, v124 offset:144
	v_mfma_f32_32x32x2_f32 v[148:163], v178, v22, v[148:163]
	ds_read_u16_d16_hi v244, v123 offset:9792
	v_permlane32_swap_b32_e32 v19, v20
	v_mfma_f32_32x32x2_f32 v[132:147], v179, v23, v[132:147]
	ds_read_b64 v[192:193], v125 offset:10192
	v_mfma_f32_32x32x2_f32 v[148:163], v179, v24, v[148:163]
	ds_read_b32 v209, v124 offset:148
	v_permlane32_swap_b32_e32 v21, v22
	v_mfma_f32_32x32x2_f32 v[132:147], v222, v25, v[132:147]
	ds_read_u16_d16_hi v245, v123 offset:10064
	v_mfma_f32_32x32x2_f32 v[148:163], v222, v27, v[148:163]
	ds_read_b64 v[194:195], v125 offset:10464
	v_permlane32_swap_b32_e32 v23, v24
	v_mfma_f32_32x32x2_f32 v[132:147], v223, v28, v[132:147]
	ds_read_b32 v210, v124 offset:152
	v_mfma_f32_32x32x2_f32 v[148:163], v223, v29, v[148:163]
	ds_read_u16_d16_hi v246, v123 offset:10336
	v_permlane32_swap_b32_e32 v25, v27
	v_mfma_f32_32x32x2_f32 v[132:147], v224, v30, v[132:147]
	ds_read_b64 v[196:197], v125 offset:10736
	v_mfma_f32_32x32x2_f32 v[148:163], v224, v31, v[148:163]
	ds_read_b32 v211, v124 offset:156
; #define GDN_LOADROW(buf, rr_, i_) do { _Pragma("unroll") for (int j4 = 0; j4 < ((i_) + 3) / 4; ++j4) buf[j4] = *(const f32x4*)(Lm + (i_) * GP_LSTR + 4 * j4); rr_ = bf2f(*(const bf16*)(xsrc + (i_) * GP_STR * 2)) * scl[i_]; } while (0)
; template <int STRIP> __device__ __forceinline__ void ph_gdn_prep_fast(const bf16* __restrict__ proj, const float* __restrict__ small, const float* __restrict__ conv_w, const float* __restrict__ a_log, const float* __restrict__ dt_bias, ...
;     ...
; #pragma unroll
;             for (int i = 0; i < 64; i += 2) {
;                 GDN_LOADROW(bB, rB, i + 1);
;                 GDN_ROW(bA, rA, i);
;                 if (i + 2 < 64) GDN_LOADROW(bA, rA, i + 2);
;                 GDN_ROW(bB, rB, i + 1);
;             }
	v_permlane32_swap_b32_e32 v28, v29
	v_mfma_f32_32x32x2_f32 v[132:147], v225, v32, v[132:147]
	ds_read_u16_d16_hi v247, v123 offset:10608
	v_mfma_f32_32x32x2_f32 v[148:163], v225, v33, v[148:163]
	ds_read_b64 v[198:199], v125 offset:11008
	v_permlane32_swap_b32_e32 v30, v31
	v_mfma_f32_32x32x2_f32 v[132:147], v226, v34, v[132:147]
	ds_read_b32 v212, v124 offset:160
	v_mfma_f32_32x32x2_f32 v[148:163], v226, v35, v[148:163]
	ds_read_u16_d16_hi v248, v123 offset:10880
	v_permlane32_swap_b32_e32 v32, v33
	v_mfma_f32_32x32x2_f32 v[132:147], v227, v36, v[132:147]
	ds_read_b64 v[200:201], v125 offset:11280
	v_mfma_f32_32x32x2_f32 v[148:163], v227, v37, v[148:163]
	ds_read_b64 v[202:203], v125 offset:11312
	v_permlane32_swap_b32_e32 v34, v35
	v_mfma_f32_32x32x2_f32 v[132:147], v228, v38, v[132:147]
	ds_read_b32 v213, v124 offset:164
	v_mfma_f32_32x32x2_f32 v[148:163], v228, v39, v[148:163]
	ds_read_u16_d16_hi v249, v123 offset:11152
	v_permlane32_swap_b32_e32 v36, v37
	v_mfma_f32_32x32x2_f32 v[132:147], v229, v40, v[132:147]
	ds_read_b64 v[204:205], v125 offset:11552
	v_mfma_f32_32x32x2_f32 v[148:163], v229, v41, v[148:163]
	ds_read_b64 v[206:207], v125 offset:11584
	v_permlane32_swap_b32_e32 v38, v39
	v_permlane32_swap_b32_e32 v40, v41
	s_nop 7
	s_nop 7
	s_nop 3
	v_permlane32_swap_b32_e32 v132, v148
	v_permlane32_swap_b32_e32 v133, v149
	v_permlane32_swap_b32_e32 v134, v150
	v_permlane32_swap_b32_e32 v135, v151
	v_permlane32_swap_b32_e32 v136, v152
	v_permlane32_swap_b32_e32 v137, v153
	v_permlane32_swap_b32_e32 v138, v154
	v_permlane32_swap_b32_e32 v139, v155
	v_permlane32_swap_b32_e32 v140, v156
	v_permlane32_swap_b32_e32 v141, v157
	v_permlane32_swap_b32_e32 v142, v158
	v_permlane32_swap_b32_e32 v143, v159
	v_permlane32_swap_b32_e32 v144, v160
	v_permlane32_swap_b32_e32 v145, v161
	v_permlane32_swap_b32_e32 v146, v162
	v_permlane32_swap_b32_e32 v147, v163
	s_waitcnt lgkmcnt(15)
	v_fma_f32 v116, v181, v252, -v132
	v_add_f32_e32 v42, 0, v116
	s_waitcnt lgkmcnt(15)
	v_fma_f32 v116, v182, v253, -v133
	v_fmac_f32_dpp v116, -v170, v42 quad_perm:[0,0,0,0] row_mask:0xf bank_mask:0xf
	v_add_f32_e32 v43, 0, v116
	s_waitcnt lgkmcnt(15)
	v_fma_f32 v116, v183, v126, -v134
	v_fmac_f32_dpp v116, -v186, v42 quad_perm:[0,0,0,0] row_mask:0xf bank_mask:0xf
	v_mul_f32_dpp v117, -v187, v43 quad_perm:[0,0,0,0] row_mask:0xf bank_mask:0xf
	ds_read_b32 v214, v124 offset:168
	v_add_f32_e32 v44, v117, v116
	s_waitcnt lgkmcnt(15)
	v_fma_f32 v116, v185, v127, -v135
	v_fmac_f32_dpp v116, -v188, v42 quad_perm:[0,0,0,0] row_mask:0xf bank_mask:0xf
	v_mul_f32_dpp v117, -v189, v43 quad_perm:[0,0,0,0] row_mask:0xf bank_mask:0xf
	v_mul_f32_dpp v118, -v188, v44 quad_perm:[1,1,1,1] row_mask:0xf bank_mask:0xf
	ds_read_u16_d16_hi v250, v123 offset:11424
	v_add_f32_e32 v121, v117, v116
	v_add_f32_e32 v45, v118, v121
	s_waitcnt lgkmcnt(15)
	v_fma_f32 v116, v208, v244, -v148
	v_fmac_f32_dpp v116, -v190, v42 quad_perm:[0,0,0,0] row_mask:0xf bank_mask:0xf
	v_mul_f32_dpp v117, -v191, v43 quad_perm:[0,0,0,0] row_mask:0xf bank_mask:0xf
	v_mul_f32_dpp v118, -v190, v44 quad_perm:[1,1,1,1] row_mask:0xf bank_mask:0xf
	ds_read_b64 v[164:165], v125 offset:11824
	v_mul_f32_dpp v119, -v191, v45 quad_perm:[1,1,1,1] row_mask:0xf bank_mask:0xf
	v_add_f32_e32 v121, v117, v116
	v_add_f32_e32 v122, v118, v119
	v_add_f32_e32 v46, v122, v121
	s_waitcnt lgkmcnt(15)
	v_fma_f32 v116, v209, v245, -v149
	v_fmac_f32_dpp v116, -v192, v42 quad_perm:[0,0,0,0] row_mask:0xf bank_mask:0xf
	v_mul_f32_dpp v117, -v193, v43 quad_perm:[0,0,0,0] row_mask:0xf bank_mask:0xf
	ds_read_b64 v[166:167], v125 offset:11856
	v_mul_f32_dpp v118, -v192, v44 quad_perm:[1,1,1,1] row_mask:0xf bank_mask:0xf
	v_mul_f32_dpp v119, -v193, v45 quad_perm:[1,1,1,1] row_mask:0xf bank_mask:0xf
	v_fmac_f32_dpp v116, -v192, v46 quad_perm:[2,2,2,2] row_mask:0xf bank_mask:0xf
	ds_read_b32 v215, v124 offset:172
	v_add_f32_e32 v121, v117, v116
	v_add_f32_e32 v122, v118, v119
	v_add_f32_e32 v47, v122, v121
	s_waitcnt lgkmcnt(15)
	v_fma_f32 v116, v210, v246, -v150
	v_fmac_f32_dpp v116, -v194, v42 quad_perm:[0,0,0,0] row_mask:0xf bank_mask:0xf
	v_mul_f32_dpp v117, -v195, v43 quad_perm:[0,0,0,0] row_mask:0xf bank_mask:0xf
	v_mul_f32_dpp v118, -v194, v44 quad_perm:[1,1,1,1] row_mask:0xf bank_mask:0xf
	ds_read_u16_d16_hi v251, v123 offset:11696
	v_mul_f32_dpp v119, -v195, v45 quad_perm:[1,1,1,1] row_mask:0xf bank_mask:0xf
	v_fmac_f32_dpp v116, -v194, v46 quad_perm:[2,2,2,2] row_mask:0xf bank_mask:0xf
	v_fmac_f32_dpp v117, -v195, v47 quad_perm:[2,2,2,2] row_mask:0xf bank_mask:0xf
	ds_read_b64 v[168:169], v125 offset:12096
	v_add_f32_e32 v121, v117, v116
	v_add_f32_e32 v122, v118, v119
	v_add_f32_e32 v48, v122, v121
	s_waitcnt lgkmcnt(15)
	v_fma_f32 v116, v211, v247, -v151
	v_fmac_f32_dpp v116, -v196, v42 quad_perm:[0,0,0,0] row_mask:0xf bank_mask:0xf
	v_mul_f32_dpp v117, -v197, v43 quad_perm:[0,0,0,0] row_mask:0xf bank_mask:0xf
	v_mul_f32_dpp v118, -v196, v44 quad_perm:[1,1,1,1] row_mask:0xf bank_mask:0xf
	ds_read_b64 v[172:173], v125 offset:12128
	v_mul_f32_dpp v119, -v197, v45 quad_perm:[1,1,1,1] row_mask:0xf bank_mask:0xf
	v_fmac_f32_dpp v116, -v196, v46 quad_perm:[2,2,2,2] row_mask:0xf bank_mask:0xf
	v_fmac_f32_dpp v117, -v197, v47 quad_perm:[2,2,2,2] row_mask:0xf bank_mask:0xf
	ds_read_b32 v216, v124 offset:176
	v_fmac_f32_dpp v118, -v196, v48 quad_perm:[3,3,3,3] row_mask:0xf bank_mask:0xf
	v_add_f32_e32 v121, v117, v116
	v_add_f32_e32 v122, v118, v119
	v_add_f32_e32 v49, v122, v121
	s_waitcnt lgkmcnt(15)
; #define GDN_LOADROW(buf, rr_, i_) do { _Pragma("unroll") for (int j4 = 0; j4 < ((i_) + 3) / 4; ++j4) buf[j4] = *(const f32x4*)(Lm + (i_) * GP_LSTR + 4 * j4); rr_ = bf2f(*(const bf16*)(xsrc + (i_) * GP_STR * 2)) * scl[i_]; } while (0)
; template <int STRIP> __device__ __forceinline__ void ph_gdn_prep_fast(const bf16* __restrict__ proj, const float* __restrict__ small, const float* __restrict__ conv_w, const float* __restrict__ a_log, const float* __restrict__ dt_bias, ...
;     ...
; #pragma unroll
;             for (int i = 0; i < 64; i += 2) {
;                 GDN_LOADROW(bB, rB, i + 1);
;                 GDN_ROW(bA, rA, i);
;                 if (i + 2 < 64) GDN_LOADROW(bA, rA, i + 2);
;                 GDN_ROW(bB, rB, i + 1);
;             }
	v_fma_f32 v116, v212, v248, -v136
	v_fmac_f32_dpp v116, -v198, v42 quad_perm:[0,0,0,0] row_mask:0xf bank_mask:0xf
	v_mul_f32_dpp v117, -v199, v43 quad_perm:[0,0,0,0] row_mask:0xf bank_mask:0xf
	ds_read_u16_d16_hi v252, v123 offset:11968
	v_mul_f32_dpp v118, -v198, v44 quad_perm:[1,1,1,1] row_mask:0xf bank_mask:0xf
	v_mul_f32_dpp v119, -v199, v45 quad_perm:[1,1,1,1] row_mask:0xf bank_mask:0xf
	v_fmac_f32_dpp v116, -v198, v46 quad_perm:[2,2,2,2] row_mask:0xf bank_mask:0xf
	ds_read_b64 v[174:175], v125 offset:12368
	v_fmac_f32_dpp v117, -v199, v47 quad_perm:[2,2,2,2] row_mask:0xf bank_mask:0xf
	v_fmac_f32_dpp v118, -v198, v48 quad_perm:[3,3,3,3] row_mask:0xf bank_mask:0xf
	v_fmac_f32_dpp v119, -v199, v49 quad_perm:[3,3,3,3] row_mask:0xf bank_mask:0xf
	ds_read_b64 v[176:177], v125 offset:12400
	v_add_f32_e32 v121, v117, v116
	v_add_f32_e32 v122, v118, v119
	v_add_f32_e32 v50, v122, v121
	s_waitcnt lgkmcnt(14)
	v_fma_f32 v116, v213, v249, -v137
	v_fmac_f32_dpp v116, -v200, v42 quad_perm:[0,0,0,0] row_mask:0xf bank_mask:0xf
	v_mul_f32_dpp v117, -v201, v43 quad_perm:[0,0,0,0] row_mask:0xf bank_mask:0xf
	v_mul_f32_dpp v118, -v200, v44 quad_perm:[1,1,1,1] row_mask:0xf bank_mask:0xf
	ds_read_b32 v217, v124 offset:180
	v_mul_f32_dpp v119, -v201, v45 quad_perm:[1,1,1,1] row_mask:0xf bank_mask:0xf
	v_fmac_f32_dpp v116, -v200, v46 quad_perm:[2,2,2,2] row_mask:0xf bank_mask:0xf
	v_fmac_f32_dpp v117, -v201, v47 quad_perm:[2,2,2,2] row_mask:0xf bank_mask:0xf
	ds_read_u16_d16_hi v253, v123 offset:12240
	v_fmac_f32_dpp v118, -v200, v48 quad_perm:[3,3,3,3] row_mask:0xf bank_mask:0xf
	v_fmac_f32_dpp v119, -v201, v49 quad_perm:[3,3,3,3] row_mask:0xf bank_mask:0xf
	v_fmac_f32_dpp v116, -v202, v50 quad_perm:[0,0,0,0] row_mask:0xf bank_mask:0xf
	ds_read_b64 v[178:179], v125 offset:12640
	v_add_f32_e32 v121, v117, v116
	v_add_f32_e32 v122, v118, v119
	v_add_f32_e32 v51, v122, v121
	s_waitcnt lgkmcnt(13)
	v_fma_f32 v116, v214, v250, -v138
	v_fmac_f32_dpp v116, -v204, v42 quad_perm:[0,0,0,0] row_mask:0xf bank_mask:0xf
	v_mul_f32_dpp v117, -v205, v43 quad_perm:[0,0,0,0] row_mask:0xf bank_mask:0xf
	v_mul_f32_dpp v118, -v204, v44 quad_perm:[1,1,1,1] row_mask:0xf bank_mask:0xf
	ds_read_b64 v[222:223], v125 offset:12672
	v_mul_f32_dpp v119, -v205, v45 quad_perm:[1,1,1,1] row_mask:0xf bank_mask:0xf
	v_fmac_f32_dpp v116, -v204, v46 quad_perm:[2,2,2,2] row_mask:0xf bank_mask:0xf
	v_fmac_f32_dpp v117, -v205, v47 quad_perm:[2,2,2,2] row_mask:0xf bank_mask:0xf
	ds_read_b32 v218, v124 offset:184
	v_fmac_f32_dpp v118, -v204, v48 quad_perm:[3,3,3,3] row_mask:0xf bank_mask:0xf
	v_fmac_f32_dpp v119, -v205, v49 quad_perm:[3,3,3,3] row_mask:0xf bank_mask:0xf
	v_fmac_f32_dpp v116, -v206, v50 quad_perm:[0,0,0,0] row_mask:0xf bank_mask:0xf
	ds_read_u16_d16_hi v126, v123 offset:12512
	v_fmac_f32_dpp v117, -v207, v51 quad_perm:[0,0,0,0] row_mask:0xf bank_mask:0xf
	v_add_f32_e32 v121, v117, v116
	v_add_f32_e32 v122, v118, v119
	v_add_f32_e32 v52, v122, v121
	s_waitcnt lgkmcnt(12)
	v_fma_f32 v116, v215, v251, -v139
	v_fmac_f32_dpp v116, -v164, v42 quad_perm:[0,0,0,0] row_mask:0xf bank_mask:0xf
	v_mul_f32_dpp v117, -v165, v43 quad_perm:[0,0,0,0] row_mask:0xf bank_mask:0xf
	ds_read_b64 v[224:225], v125 offset:12912
	v_mul_f32_dpp v118, -v164, v44 quad_perm:[1,1,1,1] row_mask:0xf bank_mask:0xf
	v_mul_f32_dpp v119, -v165, v45 quad_perm:[1,1,1,1] row_mask:0xf bank_mask:0xf
	v_fmac_f32_dpp v116, -v164, v46 quad_perm:[2,2,2,2] row_mask:0xf bank_mask:0xf
	ds_read_b64 v[226:227], v125 offset:12944
	v_fmac_f32_dpp v117, -v165, v47 quad_perm:[2,2,2,2] row_mask:0xf bank_mask:0xf
	v_fmac_f32_dpp v118, -v164, v48 quad_perm:[3,3,3,3] row_mask:0xf bank_mask:0xf
	v_fmac_f32_dpp v119, -v165, v49 quad_perm:[3,3,3,3] row_mask:0xf bank_mask:0xf
	ds_read_b32 v219, v124 offset:188
	v_fmac_f32_dpp v116, -v166, v50 quad_perm:[0,0,0,0] row_mask:0xf bank_mask:0xf
	v_fmac_f32_dpp v117, -v167, v51 quad_perm:[0,0,0,0] row_mask:0xf bank_mask:0xf
	v_fmac_f32_dpp v118, -v166, v52 quad_perm:[1,1,1,1] row_mask:0xf bank_mask:0xf
	ds_read_u16_d16_hi v127, v123 offset:12784
	v_add_f32_e32 v121, v117, v116
	v_add_f32_e32 v122, v118, v119
	v_add_f32_e32 v53, v122, v121
	s_waitcnt lgkmcnt(12)
	v_fma_f32 v116, v216, v252, -v152
	v_fmac_f32_dpp v116, -v168, v42 quad_perm:[0,0,0,0] row_mask:0xf bank_mask:0xf
	v_mul_f32_dpp v117, -v169, v43 quad_perm:[0,0,0,0] row_mask:0xf bank_mask:0xf
	v_mul_f32_dpp v118, -v168, v44 quad_perm:[1,1,1,1] row_mask:0xf bank_mask:0xf
	ds_read_b64 v[228:229], v125 offset:13184
	v_mul_f32_dpp v119, -v169, v45 quad_perm:[1,1,1,1] row_mask:0xf bank_mask:0xf
	v_fmac_f32_dpp v116, -v168, v46 quad_perm:[2,2,2,2] row_mask:0xf bank_mask:0xf
	v_fmac_f32_dpp v117, -v169, v47 quad_perm:[2,2,2,2] row_mask:0xf bank_mask:0xf
	ds_read_b64 v[170:171], v125 offset:13216
	v_fmac_f32_dpp v118, -v168, v48 quad_perm:[3,3,3,3] row_mask:0xf bank_mask:0xf
	v_fmac_f32_dpp v119, -v169, v49 quad_perm:[3,3,3,3] row_mask:0xf bank_mask:0xf
	v_fmac_f32_dpp v116, -v172, v50 quad_perm:[0,0,0,0] row_mask:0xf bank_mask:0xf
	ds_read_b32 v220, v124 offset:192
	v_fmac_f32_dpp v117, -v173, v51 quad_perm:[0,0,0,0] row_mask:0xf bank_mask:0xf
	v_fmac_f32_dpp v118, -v172, v52 quad_perm:[1,1,1,1] row_mask:0xf bank_mask:0xf
	v_fmac_f32_dpp v119, -v173, v53 quad_perm:[1,1,1,1] row_mask:0xf bank_mask:0xf
	ds_read_u16_d16_hi v244, v123 offset:13056
	v_add_f32_e32 v121, v117, v116
	v_add_f32_e32 v122, v118, v119
	v_add_f32_e32 v54, v122, v121
	s_waitcnt lgkmcnt(12)
; #define GDN_LOADROW(buf, rr_, i_) do { _Pragma("unroll") for (int j4 = 0; j4 < ((i_) + 3) / 4; ++j4) buf[j4] = *(const f32x4*)(Lm + (i_) * GP_LSTR + 4 * j4); rr_ = bf2f(*(const bf16*)(xsrc + (i_) * GP_STR * 2)) * scl[i_]; } while (0)
; template <int STRIP> __device__ __forceinline__ void ph_gdn_prep_fast(const bf16* __restrict__ proj, const float* __restrict__ small, const float* __restrict__ conv_w, const float* __restrict__ a_log, const float* __restrict__ dt_bias, ...
;     ...
; #pragma unroll
;             for (int i = 0; i < 64; i += 2) {
;                 GDN_LOADROW(bB, rB, i + 1);
;                 GDN_ROW(bA, rA, i);
;                 if (i + 2 < 64) GDN_LOADROW(bA, rA, i + 2);
;                 GDN_ROW(bB, rB, i + 1);
;             }
	v_fma_f32 v116, v217, v253, -v153
	v_fmac_f32_dpp v116, -v174, v42 quad_perm:[0,0,0,0] row_mask:0xf bank_mask:0xf
	v_mul_f32_dpp v117, -v175, v43 quad_perm:[0,0,0,0] row_mask:0xf bank_mask:0xf
	v_mul_f32_dpp v118, -v174, v44 quad_perm:[1,1,1,1] row_mask:0xf bank_mask:0xf
	ds_read_b64 v[186:187], v125 offset:13456
	v_mul_f32_dpp v119, -v175, v45 quad_perm:[1,1,1,1] row_mask:0xf bank_mask:0xf
	v_fmac_f32_dpp v116, -v174, v46 quad_perm:[2,2,2,2] row_mask:0xf bank_mask:0xf
	v_fmac_f32_dpp v117, -v175, v47 quad_perm:[2,2,2,2] row_mask:0xf bank_mask:0xf
	ds_read_b64 v[188:189], v125 offset:13488
	v_fmac_f32_dpp v118, -v174, v48 quad_perm:[3,3,3,3] row_mask:0xf bank_mask:0xf
	v_fmac_f32_dpp v119, -v175, v49 quad_perm:[3,3,3,3] row_mask:0xf bank_mask:0xf
	v_fmac_f32_dpp v116, -v176, v50 quad_perm:[0,0,0,0] row_mask:0xf bank_mask:0xf
	ds_read_b64 v[190:191], v125 offset:13520
	v_fmac_f32_dpp v117, -v177, v51 quad_perm:[0,0,0,0] row_mask:0xf bank_mask:0xf
	v_fmac_f32_dpp v118, -v176, v52 quad_perm:[1,1,1,1] row_mask:0xf bank_mask:0xf
	v_fmac_f32_dpp v119, -v177, v53 quad_perm:[1,1,1,1] row_mask:0xf bank_mask:0xf
	ds_read_b32 v221, v124 offset:196
	v_fmac_f32_dpp v116, -v176, v54 quad_perm:[2,2,2,2] row_mask:0xf bank_mask:0xf
	v_add_f32_e32 v121, v117, v116
	v_add_f32_e32 v122, v118, v119
	v_add_f32_e32 v55, v122, v121
	s_waitcnt lgkmcnt(12)
	v_fma_f32 v116, v218, v126, -v154
	v_fmac_f32_dpp v116, -v178, v42 quad_perm:[0,0,0,0] row_mask:0xf bank_mask:0xf
	v_mul_f32_dpp v117, -v179, v43 quad_perm:[0,0,0,0] row_mask:0xf bank_mask:0xf
	ds_read_u16_d16_hi v245, v123 offset:13328
	v_mul_f32_dpp v118, -v178, v44 quad_perm:[1,1,1,1] row_mask:0xf bank_mask:0xf
	v_mul_f32_dpp v119, -v179, v45 quad_perm:[1,1,1,1] row_mask:0xf bank_mask:0xf
	v_fmac_f32_dpp v116, -v178, v46 quad_perm:[2,2,2,2] row_mask:0xf bank_mask:0xf
	ds_read_b64 v[192:193], v125 offset:13728
	v_fmac_f32_dpp v117, -v179, v47 quad_perm:[2,2,2,2] row_mask:0xf bank_mask:0xf
	v_fmac_f32_dpp v118, -v178, v48 quad_perm:[3,3,3,3] row_mask:0xf bank_mask:0xf
	v_fmac_f32_dpp v119, -v179, v49 quad_perm:[3,3,3,3] row_mask:0xf bank_mask:0xf
	ds_read_b64 v[194:195], v125 offset:13760
	v_fmac_f32_dpp v116, -v222, v50 quad_perm:[0,0,0,0] row_mask:0xf bank_mask:0xf
	v_fmac_f32_dpp v117, -v223, v51 quad_perm:[0,0,0,0] row_mask:0xf bank_mask:0xf
	v_fmac_f32_dpp v118, -v222, v52 quad_perm:[1,1,1,1] row_mask:0xf bank_mask:0xf
	ds_read_b64 v[196:197], v125 offset:13792
	v_fmac_f32_dpp v119, -v223, v53 quad_perm:[1,1,1,1] row_mask:0xf bank_mask:0xf
	v_fmac_f32_dpp v116, -v222, v54 quad_perm:[2,2,2,2] row_mask:0xf bank_mask:0xf
	v_fmac_f32_dpp v117, -v223, v55 quad_perm:[2,2,2,2] row_mask:0xf bank_mask:0xf
	ds_read_b32 v181, v124 offset:200
	v_add_f32_e32 v121, v117, v116
	v_add_f32_e32 v122, v118, v119
	v_add_f32_e32 v56, v122, v121
	s_waitcnt lgkmcnt(13)
	v_fma_f32 v116, v219, v127, -v155
	v_fmac_f32_dpp v116, -v224, v42 quad_perm:[0,0,0,0] row_mask:0xf bank_mask:0xf
	v_mul_f32_dpp v117, -v225, v43 quad_perm:[0,0,0,0] row_mask:0xf bank_mask:0xf
	v_mul_f32_dpp v118, -v224, v44 quad_perm:[1,1,1,1] row_mask:0xf bank_mask:0xf
	ds_read_u16_d16_hi v246, v123 offset:13600
	v_mul_f32_dpp v119, -v225, v45 quad_perm:[1,1,1,1] row_mask:0xf bank_mask:0xf
	v_fmac_f32_dpp v116, -v224, v46 quad_perm:[2,2,2,2] row_mask:0xf bank_mask:0xf
	v_fmac_f32_dpp v117, -v225, v47 quad_perm:[2,2,2,2] row_mask:0xf bank_mask:0xf
	ds_read_b64 v[198:199], v125 offset:14000
	v_fmac_f32_dpp v118, -v224, v48 quad_perm:[3,3,3,3] row_mask:0xf bank_mask:0xf
	v_fmac_f32_dpp v119, -v225, v49 quad_perm:[3,3,3,3] row_mask:0xf bank_mask:0xf
	v_fmac_f32_dpp v116, -v226, v50 quad_perm:[0,0,0,0] row_mask:0xf bank_mask:0xf
	ds_read_b64 v[200:201], v125 offset:14032
	v_fmac_f32_dpp v117, -v227, v51 quad_perm:[0,0,0,0] row_mask:0xf bank_mask:0xf
	v_fmac_f32_dpp v118, -v226, v52 quad_perm:[1,1,1,1] row_mask:0xf bank_mask:0xf
	v_fmac_f32_dpp v119, -v227, v53 quad_perm:[1,1,1,1] row_mask:0xf bank_mask:0xf
	ds_read_b64 v[202:203], v125 offset:14064
	v_fmac_f32_dpp v116, -v226, v54 quad_perm:[2,2,2,2] row_mask:0xf bank_mask:0xf
	v_fmac_f32_dpp v117, -v227, v55 quad_perm:[2,2,2,2] row_mask:0xf bank_mask:0xf
	v_fmac_f32_dpp v118, -v226, v56 quad_perm:[3,3,3,3] row_mask:0xf bank_mask:0xf
	ds_read_b32 v182, v124 offset:204
	v_add_f32_e32 v121, v117, v116
	v_add_f32_e32 v122, v118, v119
	v_add_f32_e32 v57, v122, v121
	s_waitcnt lgkmcnt(14)
	v_fma_f32 v116, v220, v244, -v140
	v_fmac_f32_dpp v116, -v228, v42 quad_perm:[0,0,0,0] row_mask:0xf bank_mask:0xf
	v_mul_f32_dpp v117, -v229, v43 quad_perm:[0,0,0,0] row_mask:0xf bank_mask:0xf
	v_mul_f32_dpp v118, -v228, v44 quad_perm:[1,1,1,1] row_mask:0xf bank_mask:0xf
	ds_read_u16_d16_hi v247, v123 offset:13872
	v_mul_f32_dpp v119, -v229, v45 quad_perm:[1,1,1,1] row_mask:0xf bank_mask:0xf
	v_fmac_f32_dpp v116, -v228, v46 quad_perm:[2,2,2,2] row_mask:0xf bank_mask:0xf
	v_fmac_f32_dpp v117, -v229, v47 quad_perm:[2,2,2,2] row_mask:0xf bank_mask:0xf
	ds_read_b64 v[204:205], v125 offset:14272
	v_fmac_f32_dpp v118, -v228, v48 quad_perm:[3,3,3,3] row_mask:0xf bank_mask:0xf
	v_fmac_f32_dpp v119, -v229, v49 quad_perm:[3,3,3,3] row_mask:0xf bank_mask:0xf
	v_fmac_f32_dpp v116, -v170, v50 quad_perm:[0,0,0,0] row_mask:0xf bank_mask:0xf
	ds_read_b64 v[206:207], v125 offset:14304
	v_fmac_f32_dpp v117, -v171, v51 quad_perm:[0,0,0,0] row_mask:0xf bank_mask:0xf
	v_fmac_f32_dpp v118, -v170, v52 quad_perm:[1,1,1,1] row_mask:0xf bank_mask:0xf
	v_fmac_f32_dpp v119, -v171, v53 quad_perm:[1,1,1,1] row_mask:0xf bank_mask:0xf
	ds_read_b64 v[164:165], v125 offset:14336
	v_fmac_f32_dpp v116, -v170, v54 quad_perm:[2,2,2,2] row_mask:0xf bank_mask:0xf
	v_fmac_f32_dpp v117, -v171, v55 quad_perm:[2,2,2,2] row_mask:0xf bank_mask:0xf
	v_fmac_f32_dpp v118, -v170, v56 quad_perm:[3,3,3,3] row_mask:0xf bank_mask:0xf
	ds_read_b32 v183, v124 offset:208
	v_fmac_f32_dpp v119, -v171, v57 quad_perm:[3,3,3,3] row_mask:0xf bank_mask:0xf
	v_add_f32_e32 v121, v117, v116
	v_add_f32_e32 v122, v118, v119
	v_add_f32_e32 v58, v122, v121
	s_waitcnt lgkmcnt(14)
; #define GDN_LOADROW(buf, rr_, i_) do { _Pragma("unroll") for (int j4 = 0; j4 < ((i_) + 3) / 4; ++j4) buf[j4] = *(const f32x4*)(Lm + (i_) * GP_LSTR + 4 * j4); rr_ = bf2f(*(const bf16*)(xsrc + (i_) * GP_STR * 2)) * scl[i_]; } while (0)
; template <int STRIP> __device__ __forceinline__ void ph_gdn_prep_fast(const bf16* __restrict__ proj, const float* __restrict__ small, const float* __restrict__ conv_w, const float* __restrict__ a_log, const float* __restrict__ dt_bias, ...
;     ...
; #pragma unroll
;             for (int i = 0; i < 64; i += 2) {
;                 GDN_LOADROW(bB, rB, i + 1);
;                 GDN_ROW(bA, rA, i);
;                 if (i + 2 < 64) GDN_LOADROW(bA, rA, i + 2);
;                 GDN_ROW(bB, rB, i + 1);
;             }
	v_fma_f32 v116, v221, v245, -v141
	v_fmac_f32_dpp v116, -v186, v42 quad_perm:[0,0,0,0] row_mask:0xf bank_mask:0xf
	v_mul_f32_dpp v117, -v187, v43 quad_perm:[0,0,0,0] row_mask:0xf bank_mask:0xf
	ds_read_u16_d16_hi v248, v123 offset:14144
	v_mul_f32_dpp v118, -v186, v44 quad_perm:[1,1,1,1] row_mask:0xf bank_mask:0xf
	v_mul_f32_dpp v119, -v187, v45 quad_perm:[1,1,1,1] row_mask:0xf bank_mask:0xf
	v_fmac_f32_dpp v116, -v186, v46 quad_perm:[2,2,2,2] row_mask:0xf bank_mask:0xf
	ds_read_b64 v[166:167], v125 offset:14544
	v_fmac_f32_dpp v117, -v187, v47 quad_perm:[2,2,2,2] row_mask:0xf bank_mask:0xf
	v_fmac_f32_dpp v118, -v186, v48 quad_perm:[3,3,3,3] row_mask:0xf bank_mask:0xf
	v_fmac_f32_dpp v119, -v187, v49 quad_perm:[3,3,3,3] row_mask:0xf bank_mask:0xf
	ds_read_b64 v[168:169], v125 offset:14576
	v_fmac_f32_dpp v116, -v188, v50 quad_perm:[0,0,0,0] row_mask:0xf bank_mask:0xf
	v_fmac_f32_dpp v117, -v189, v51 quad_perm:[0,0,0,0] row_mask:0xf bank_mask:0xf
	v_fmac_f32_dpp v118, -v188, v52 quad_perm:[1,1,1,1] row_mask:0xf bank_mask:0xf
	ds_read_b64 v[172:173], v125 offset:14608
	v_fmac_f32_dpp v119, -v189, v53 quad_perm:[1,1,1,1] row_mask:0xf bank_mask:0xf
	v_fmac_f32_dpp v116, -v188, v54 quad_perm:[2,2,2,2] row_mask:0xf bank_mask:0xf
	v_fmac_f32_dpp v117, -v189, v55 quad_perm:[2,2,2,2] row_mask:0xf bank_mask:0xf
	ds_read_b32 v185, v124 offset:212
	v_fmac_f32_dpp v118, -v188, v56 quad_perm:[3,3,3,3] row_mask:0xf bank_mask:0xf
	v_fmac_f32_dpp v119, -v189, v57 quad_perm:[3,3,3,3] row_mask:0xf bank_mask:0xf
	v_fmac_f32_dpp v116, -v190, v58 quad_perm:[0,0,0,0] row_mask:0xf bank_mask:0xf
	ds_read_u16_d16_hi v249, v123 offset:14416
	v_add_f32_e32 v121, v117, v116
	v_add_f32_e32 v122, v118, v119
	v_add_f32_e32 v59, v122, v121
	s_waitcnt lgkmcnt(15)
	v_fma_f32 v116, v181, v246, -v142
	v_fmac_f32_dpp v116, -v192, v42 quad_perm:[0,0,0,0] row_mask:0xf bank_mask:0xf
	v_mul_f32_dpp v117, -v193, v43 quad_perm:[0,0,0,0] row_mask:0xf bank_mask:0xf
	v_mul_f32_dpp v118, -v192, v44 quad_perm:[1,1,1,1] row_mask:0xf bank_mask:0xf
	ds_read_b64 v[174:175], v125 offset:14816
	v_mul_f32_dpp v119, -v193, v45 quad_perm:[1,1,1,1] row_mask:0xf bank_mask:0xf
	v_fmac_f32_dpp v116, -v192, v46 quad_perm:[2,2,2,2] row_mask:0xf bank_mask:0xf
	v_fmac_f32_dpp v117, -v193, v47 quad_perm:[2,2,2,2] row_mask:0xf bank_mask:0xf
	ds_read_b64 v[176:177], v125 offset:14848
	v_fmac_f32_dpp v118, -v192, v48 quad_perm:[3,3,3,3] row_mask:0xf bank_mask:0xf
	v_fmac_f32_dpp v119, -v193, v49 quad_perm:[3,3,3,3] row_mask:0xf bank_mask:0xf
	v_fmac_f32_dpp v116, -v194, v50 quad_perm:[0,0,0,0] row_mask:0xf bank_mask:0xf
	ds_read_b64 v[178:179], v125 offset:14880
	v_fmac_f32_dpp v117, -v195, v51 quad_perm:[0,0,0,0] row_mask:0xf bank_mask:0xf
	v_fmac_f32_dpp v118, -v194, v52 quad_perm:[1,1,1,1] row_mask:0xf bank_mask:0xf
	v_fmac_f32_dpp v119, -v195, v53 quad_perm:[1,1,1,1] row_mask:0xf bank_mask:0xf
	ds_read_b32 v208, v124 offset:216
	v_fmac_f32_dpp v116, -v194, v54 quad_perm:[2,2,2,2] row_mask:0xf bank_mask:0xf
	v_fmac_f32_dpp v117, -v195, v55 quad_perm:[2,2,2,2] row_mask:0xf bank_mask:0xf
	v_fmac_f32_dpp v118, -v194, v56 quad_perm:[3,3,3,3] row_mask:0xf bank_mask:0xf
	ds_read_u16_d16_hi v250, v123 offset:14688
	v_fmac_f32_dpp v119, -v195, v57 quad_perm:[3,3,3,3] row_mask:0xf bank_mask:0xf
	v_fmac_f32_dpp v116, -v196, v58 quad_perm:[0,0,0,0] row_mask:0xf bank_mask:0xf
	v_fmac_f32_dpp v117, -v197, v59 quad_perm:[0,0,0,0] row_mask:0xf bank_mask:0xf
	ds_read_b64 v[222:223], v125 offset:15088
	v_add_f32_e32 v121, v117, v116
	v_add_f32_e32 v122, v118, v119
	v_add_f32_e32 v60, v122, v121
	s_waitcnt lgkmcnt(15)
	v_fma_f32 v116, v182, v247, -v143
	v_fmac_f32_dpp v116, -v198, v42 quad_perm:[0,0,0,0] row_mask:0xf bank_mask:0xf
	v_mul_f32_dpp v117, -v199, v43 quad_perm:[0,0,0,0] row_mask:0xf bank_mask:0xf
	v_mul_f32_dpp v118, -v198, v44 quad_perm:[1,1,1,1] row_mask:0xf bank_mask:0xf
	ds_read_b64 v[224:225], v125 offset:15120
	v_mul_f32_dpp v119, -v199, v45 quad_perm:[1,1,1,1] row_mask:0xf bank_mask:0xf
	v_fmac_f32_dpp v116, -v198, v46 quad_perm:[2,2,2,2] row_mask:0xf bank_mask:0xf
	v_fmac_f32_dpp v117, -v199, v47 quad_perm:[2,2,2,2] row_mask:0xf bank_mask:0xf
	ds_read_b64 v[226:227], v125 offset:15152
	v_fmac_f32_dpp v118, -v198, v48 quad_perm:[3,3,3,3] row_mask:0xf bank_mask:0xf
	v_fmac_f32_dpp v119, -v199, v49 quad_perm:[3,3,3,3] row_mask:0xf bank_mask:0xf
	v_fmac_f32_dpp v116, -v200, v50 quad_perm:[0,0,0,0] row_mask:0xf bank_mask:0xf
	ds_read_b32 v209, v124 offset:220
	v_fmac_f32_dpp v117, -v201, v51 quad_perm:[0,0,0,0] row_mask:0xf bank_mask:0xf
	v_fmac_f32_dpp v118, -v200, v52 quad_perm:[1,1,1,1] row_mask:0xf bank_mask:0xf
	v_fmac_f32_dpp v119, -v201, v53 quad_perm:[1,1,1,1] row_mask:0xf bank_mask:0xf
	ds_read_u16_d16_hi v251, v123 offset:14960
	v_fmac_f32_dpp v116, -v200, v54 quad_perm:[2,2,2,2] row_mask:0xf bank_mask:0xf
	v_fmac_f32_dpp v117, -v201, v55 quad_perm:[2,2,2,2] row_mask:0xf bank_mask:0xf
	v_fmac_f32_dpp v118, -v200, v56 quad_perm:[3,3,3,3] row_mask:0xf bank_mask:0xf
	ds_read_b64 v[228:229], v125 offset:15360
	v_fmac_f32_dpp v119, -v201, v57 quad_perm:[3,3,3,3] row_mask:0xf bank_mask:0xf
	v_fmac_f32_dpp v116, -v202, v58 quad_perm:[0,0,0,0] row_mask:0xf bank_mask:0xf
	v_fmac_f32_dpp v117, -v203, v59 quad_perm:[0,0,0,0] row_mask:0xf bank_mask:0xf
	ds_read_b64 v[170:171], v125 offset:15392
	v_fmac_f32_dpp v118, -v202, v60 quad_perm:[1,1,1,1] row_mask:0xf bank_mask:0xf
	v_add_f32_e32 v121, v117, v116
	v_add_f32_e32 v122, v118, v119
	v_add_f32_e32 v61, v122, v121
	s_waitcnt lgkmcnt(15)
; __device__ __forceinline__ float bf2f(bf16 v) { return __uint_as_float(((unsigned)v) << 16); }
; #define GDN_LOADROW(buf, rr_, i_) do { _Pragma("unroll") for (int j4 = 0; j4 < ((i_) + 3) / 4; ++j4) buf[j4] = *(const f32x4*)(Lm + (i_) * GP_LSTR + 4 * j4); rr_ = bf2f(*(const bf16*)(xsrc + (i_) * GP_STR * 2)) * scl[i_]; } while (0)
; template <int STRIP> __device__ __forceinline__ void ph_gdn_prep_fast(const bf16* __restrict__ proj, const float* __restrict__ small, const float* __restrict__ conv_w, const float* __restrict__ a_log, const float* __restrict__ dt_bias, ...
;     ...
;             rA = bf2f(*(const bf16*)xsrc) * scl[0];
;     ...
; #pragma unroll
;             for (int i = 0; i < 64; i += 2) {
;                 GDN_LOADROW(bB, rB, i + 1);
;                 GDN_ROW(bA, rA, i);
;                 if (i + 2 < 64) GDN_LOADROW(bA, rA, i + 2);
;                 GDN_ROW(bB, rB, i + 1);
;             }
	v_fma_f32 v116, v183, v248, -v156
	v_fmac_f32_dpp v116, -v204, v42 quad_perm:[0,0,0,0] row_mask:0xf bank_mask:0xf
	v_mul_f32_dpp v117, -v205, v43 quad_perm:[0,0,0,0] row_mask:0xf bank_mask:0xf
	ds_read_b64 v[186:187], v125 offset:15424
	v_mul_f32_dpp v118, -v204, v44 quad_perm:[1,1,1,1] row_mask:0xf bank_mask:0xf
	v_mul_f32_dpp v119, -v205, v45 quad_perm:[1,1,1,1] row_mask:0xf bank_mask:0xf
	v_fmac_f32_dpp v116, -v204, v46 quad_perm:[2,2,2,2] row_mask:0xf bank_mask:0xf
	ds_read_b32 v210, v124 offset:224
	v_fmac_f32_dpp v117, -v205, v47 quad_perm:[2,2,2,2] row_mask:0xf bank_mask:0xf
	v_fmac_f32_dpp v118, -v204, v48 quad_perm:[3,3,3,3] row_mask:0xf bank_mask:0xf
	v_fmac_f32_dpp v119, -v205, v49 quad_perm:[3,3,3,3] row_mask:0xf bank_mask:0xf
	ds_read_u16_d16_hi v252, v123 offset:15232
	v_fmac_f32_dpp v116, -v206, v50 quad_perm:[0,0,0,0] row_mask:0xf bank_mask:0xf
	v_fmac_f32_dpp v117, -v207, v51 quad_perm:[0,0,0,0] row_mask:0xf bank_mask:0xf
	v_fmac_f32_dpp v118, -v206, v52 quad_perm:[1,1,1,1] row_mask:0xf bank_mask:0xf
	ds_read_b64 v[188:189], v125 offset:15632
	v_fmac_f32_dpp v119, -v207, v53 quad_perm:[1,1,1,1] row_mask:0xf bank_mask:0xf
	v_fmac_f32_dpp v116, -v206, v54 quad_perm:[2,2,2,2] row_mask:0xf bank_mask:0xf
	v_fmac_f32_dpp v117, -v207, v55 quad_perm:[2,2,2,2] row_mask:0xf bank_mask:0xf
	ds_read_b64 v[190:191], v125 offset:15664
	v_fmac_f32_dpp v118, -v206, v56 quad_perm:[3,3,3,3] row_mask:0xf bank_mask:0xf
	v_fmac_f32_dpp v119, -v207, v57 quad_perm:[3,3,3,3] row_mask:0xf bank_mask:0xf
	v_fmac_f32_dpp v116, -v164, v58 quad_perm:[0,0,0,0] row_mask:0xf bank_mask:0xf
	ds_read_b64 v[192:193], v125 offset:15696
	v_fmac_f32_dpp v117, -v165, v59 quad_perm:[0,0,0,0] row_mask:0xf bank_mask:0xf
	v_fmac_f32_dpp v118, -v164, v60 quad_perm:[1,1,1,1] row_mask:0xf bank_mask:0xf
	v_fmac_f32_dpp v119, -v165, v61 quad_perm:[1,1,1,1] row_mask:0xf bank_mask:0xf
	ds_read_b64 v[194:195], v125 offset:15728
	v_add_f32_e32 v121, v117, v116
	v_add_f32_e32 v122, v118, v119
	v_add_f32_e32 v62, v122, v121
	s_waitcnt lgkmcnt(15)
	v_fma_f32 v116, v185, v249, -v157
	v_fmac_f32_dpp v116, -v166, v42 quad_perm:[0,0,0,0] row_mask:0xf bank_mask:0xf
	v_mul_f32_dpp v117, -v167, v43 quad_perm:[0,0,0,0] row_mask:0xf bank_mask:0xf
	v_mul_f32_dpp v118, -v166, v44 quad_perm:[1,1,1,1] row_mask:0xf bank_mask:0xf
	ds_read_b32 v211, v124 offset:228
	v_mul_f32_dpp v119, -v167, v45 quad_perm:[1,1,1,1] row_mask:0xf bank_mask:0xf
	v_fmac_f32_dpp v116, -v166, v46 quad_perm:[2,2,2,2] row_mask:0xf bank_mask:0xf
	v_fmac_f32_dpp v117, -v167, v47 quad_perm:[2,2,2,2] row_mask:0xf bank_mask:0xf
	ds_read_u16_d16_hi v253, v123 offset:15504
	v_fmac_f32_dpp v118, -v166, v48 quad_perm:[3,3,3,3] row_mask:0xf bank_mask:0xf
	v_fmac_f32_dpp v119, -v167, v49 quad_perm:[3,3,3,3] row_mask:0xf bank_mask:0xf
	v_fmac_f32_dpp v116, -v168, v50 quad_perm:[0,0,0,0] row_mask:0xf bank_mask:0xf
	ds_read_b64 v[196:197], v125 offset:15904
	v_fmac_f32_dpp v117, -v169, v51 quad_perm:[0,0,0,0] row_mask:0xf bank_mask:0xf
	v_fmac_f32_dpp v118, -v168, v52 quad_perm:[1,1,1,1] row_mask:0xf bank_mask:0xf
	v_fmac_f32_dpp v119, -v169, v53 quad_perm:[1,1,1,1] row_mask:0xf bank_mask:0xf
	ds_read_b64 v[198:199], v125 offset:15936
	v_fmac_f32_dpp v116, -v168, v54 quad_perm:[2,2,2,2] row_mask:0xf bank_mask:0xf
	v_fmac_f32_dpp v117, -v169, v55 quad_perm:[2,2,2,2] row_mask:0xf bank_mask:0xf
	v_fmac_f32_dpp v118, -v168, v56 quad_perm:[3,3,3,3] row_mask:0xf bank_mask:0xf
	ds_read_b64 v[200:201], v125 offset:15968
	v_fmac_f32_dpp v119, -v169, v57 quad_perm:[3,3,3,3] row_mask:0xf bank_mask:0xf
	v_fmac_f32_dpp v116, -v172, v58 quad_perm:[0,0,0,0] row_mask:0xf bank_mask:0xf
	v_fmac_f32_dpp v117, -v173, v59 quad_perm:[0,0,0,0] row_mask:0xf bank_mask:0xf
	ds_read_b64 v[202:203], v125 offset:16000
	v_fmac_f32_dpp v118, -v172, v60 quad_perm:[1,1,1,1] row_mask:0xf bank_mask:0xf
	v_fmac_f32_dpp v119, -v173, v61 quad_perm:[1,1,1,1] row_mask:0xf bank_mask:0xf
	v_fmac_f32_dpp v116, -v172, v62 quad_perm:[2,2,2,2] row_mask:0xf bank_mask:0xf
	ds_read_b32 v212, v124 offset:232
	v_add_f32_e32 v121, v117, v116
	v_add_f32_e32 v122, v118, v119
	v_add_f32_e32 v63, v122, v121
	s_waitcnt lgkmcnt(15)
	v_fma_f32 v116, v208, v250, -v158
	v_fmac_f32_dpp v116, -v174, v42 quad_perm:[0,0,0,0] row_mask:0xf bank_mask:0xf
	v_mul_f32_dpp v117, -v175, v43 quad_perm:[0,0,0,0] row_mask:0xf bank_mask:0xf
	v_mul_f32_dpp v118, -v174, v44 quad_perm:[1,1,1,1] row_mask:0xf bank_mask:0xf
	ds_read_u16_d16_hi v126, v123 offset:15776
	v_mul_f32_dpp v119, -v175, v45 quad_perm:[1,1,1,1] row_mask:0xf bank_mask:0xf
	v_fmac_f32_dpp v116, -v174, v46 quad_perm:[2,2,2,2] row_mask:0xf bank_mask:0xf
	v_fmac_f32_dpp v117, -v175, v47 quad_perm:[2,2,2,2] row_mask:0xf bank_mask:0xf
	ds_read_b64 v[204:205], v125 offset:16176
	v_fmac_f32_dpp v118, -v174, v48 quad_perm:[3,3,3,3] row_mask:0xf bank_mask:0xf
	v_fmac_f32_dpp v119, -v175, v49 quad_perm:[3,3,3,3] row_mask:0xf bank_mask:0xf
	v_fmac_f32_dpp v116, -v176, v50 quad_perm:[0,0,0,0] row_mask:0xf bank_mask:0xf
	ds_read_b64 v[206:207], v125 offset:16208
	v_fmac_f32_dpp v117, -v177, v51 quad_perm:[0,0,0,0] row_mask:0xf bank_mask:0xf
	v_fmac_f32_dpp v118, -v176, v52 quad_perm:[1,1,1,1] row_mask:0xf bank_mask:0xf
	v_fmac_f32_dpp v119, -v177, v53 quad_perm:[1,1,1,1] row_mask:0xf bank_mask:0xf
	ds_read_b64 v[164:165], v125 offset:16240
	v_fmac_f32_dpp v116, -v176, v54 quad_perm:[2,2,2,2] row_mask:0xf bank_mask:0xf
	v_fmac_f32_dpp v117, -v177, v55 quad_perm:[2,2,2,2] row_mask:0xf bank_mask:0xf
	v_fmac_f32_dpp v118, -v176, v56 quad_perm:[3,3,3,3] row_mask:0xf bank_mask:0xf
	ds_read_b64 v[166:167], v125 offset:16272
	v_fmac_f32_dpp v119, -v177, v57 quad_perm:[3,3,3,3] row_mask:0xf bank_mask:0xf
	v_fmac_f32_dpp v116, -v178, v58 quad_perm:[0,0,0,0] row_mask:0xf bank_mask:0xf
	v_fmac_f32_dpp v117, -v179, v59 quad_perm:[0,0,0,0] row_mask:0xf bank_mask:0xf
	ds_read_b32 v213, v124 offset:236
	v_fmac_f32_dpp v118, -v178, v60 quad_perm:[1,1,1,1] row_mask:0xf bank_mask:0xf
	v_fmac_f32_dpp v119, -v179, v61 quad_perm:[1,1,1,1] row_mask:0xf bank_mask:0xf
	v_fmac_f32_dpp v116, -v178, v62 quad_perm:[2,2,2,2] row_mask:0xf bank_mask:0xf
	ds_read_u16_d16_hi v127, v123 offset:16048
	v_fmac_f32_dpp v117, -v179, v63 quad_perm:[2,2,2,2] row_mask:0xf bank_mask:0xf
	v_add_f32_e32 v121, v117, v116
	v_add_f32_e32 v122, v118, v119
	v_add_f32_e32 v64, v122, v121
	s_waitcnt lgkmcnt(15)
; __device__ __forceinline__ float bf2f(bf16 v) { return __uint_as_float(((unsigned)v) << 16); }
; #define GDN_LOADROW(buf, rr_, i_) do { _Pragma("unroll") for (int j4 = 0; j4 < ((i_) + 3) / 4; ++j4) buf[j4] = *(const f32x4*)(Lm + (i_) * GP_LSTR + 4 * j4); rr_ = bf2f(*(const bf16*)(xsrc + (i_) * GP_STR * 2)) * scl[i_]; } while (0)
; template <int STRIP> __device__ __forceinline__ void ph_gdn_prep_fast(const bf16* __restrict__ proj, const float* __restrict__ small, const float* __restrict__ conv_w, const float* __restrict__ a_log, const float* __restrict__ dt_bias, ...
;     ...
;             rA = bf2f(*(const bf16*)xsrc) * scl[0];
;     ...
; #pragma unroll
;             for (int i = 0; i < 64; i += 2) {
;                 GDN_LOADROW(bB, rB, i + 1);
;                 GDN_ROW(bA, rA, i);
;                 if (i + 2 < 64) GDN_LOADROW(bA, rA, i + 2);
;                 GDN_ROW(bB, rB, i + 1);
;             }
	v_fma_f32 v116, v209, v251, -v159
	v_fmac_f32_dpp v116, -v222, v42 quad_perm:[0,0,0,0] row_mask:0xf bank_mask:0xf
	v_mul_f32_dpp v117, -v223, v43 quad_perm:[0,0,0,0] row_mask:0xf bank_mask:0xf
	v_mul_f32_dpp v118, -v222, v44 quad_perm:[1,1,1,1] row_mask:0xf bank_mask:0xf
	v_mul_f32_dpp v119, -v223, v45 quad_perm:[1,1,1,1] row_mask:0xf bank_mask:0xf
	v_fmac_f32_dpp v116, -v222, v46 quad_perm:[2,2,2,2] row_mask:0xf bank_mask:0xf
	v_fmac_f32_dpp v117, -v223, v47 quad_perm:[2,2,2,2] row_mask:0xf bank_mask:0xf
	v_fmac_f32_dpp v118, -v222, v48 quad_perm:[3,3,3,3] row_mask:0xf bank_mask:0xf
	v_fmac_f32_dpp v119, -v223, v49 quad_perm:[3,3,3,3] row_mask:0xf bank_mask:0xf
	v_fmac_f32_dpp v116, -v224, v50 quad_perm:[0,0,0,0] row_mask:0xf bank_mask:0xf
	v_fmac_f32_dpp v117, -v225, v51 quad_perm:[0,0,0,0] row_mask:0xf bank_mask:0xf
	v_fmac_f32_dpp v118, -v224, v52 quad_perm:[1,1,1,1] row_mask:0xf bank_mask:0xf
	v_fmac_f32_dpp v119, -v225, v53 quad_perm:[1,1,1,1] row_mask:0xf bank_mask:0xf
	v_fmac_f32_dpp v116, -v224, v54 quad_perm:[2,2,2,2] row_mask:0xf bank_mask:0xf
	v_fmac_f32_dpp v117, -v225, v55 quad_perm:[2,2,2,2] row_mask:0xf bank_mask:0xf
	v_fmac_f32_dpp v118, -v224, v56 quad_perm:[3,3,3,3] row_mask:0xf bank_mask:0xf
	v_fmac_f32_dpp v119, -v225, v57 quad_perm:[3,3,3,3] row_mask:0xf bank_mask:0xf
	v_fmac_f32_dpp v116, -v226, v58 quad_perm:[0,0,0,0] row_mask:0xf bank_mask:0xf
	v_fmac_f32_dpp v117, -v227, v59 quad_perm:[0,0,0,0] row_mask:0xf bank_mask:0xf
	v_fmac_f32_dpp v118, -v226, v60 quad_perm:[1,1,1,1] row_mask:0xf bank_mask:0xf
	v_fmac_f32_dpp v119, -v227, v61 quad_perm:[1,1,1,1] row_mask:0xf bank_mask:0xf
	v_fmac_f32_dpp v116, -v226, v62 quad_perm:[2,2,2,2] row_mask:0xf bank_mask:0xf
	v_fmac_f32_dpp v117, -v227, v63 quad_perm:[2,2,2,2] row_mask:0xf bank_mask:0xf
	v_fmac_f32_dpp v118, -v226, v64 quad_perm:[3,3,3,3] row_mask:0xf bank_mask:0xf
	v_add_f32_e32 v121, v117, v116
	v_add_f32_e32 v122, v118, v119
	v_add_f32_e32 v65, v122, v121
	s_waitcnt lgkmcnt(15)
	v_fma_f32 v116, v210, v252, -v144
	v_fmac_f32_dpp v116, -v228, v42 quad_perm:[0,0,0,0] row_mask:0xf bank_mask:0xf
	v_mul_f32_dpp v117, -v229, v43 quad_perm:[0,0,0,0] row_mask:0xf bank_mask:0xf
	v_mul_f32_dpp v118, -v228, v44 quad_perm:[1,1,1,1] row_mask:0xf bank_mask:0xf
	ds_read_b64 v[168:169], v125 offset:16448
	v_mul_f32_dpp v119, -v229, v45 quad_perm:[1,1,1,1] row_mask:0xf bank_mask:0xf
	v_fmac_f32_dpp v116, -v228, v46 quad_perm:[2,2,2,2] row_mask:0xf bank_mask:0xf
	v_fmac_f32_dpp v117, -v229, v47 quad_perm:[2,2,2,2] row_mask:0xf bank_mask:0xf
	ds_read_b64 v[172:173], v125 offset:16480
	v_fmac_f32_dpp v118, -v228, v48 quad_perm:[3,3,3,3] row_mask:0xf bank_mask:0xf
	v_fmac_f32_dpp v119, -v229, v49 quad_perm:[3,3,3,3] row_mask:0xf bank_mask:0xf
	v_fmac_f32_dpp v116, -v170, v50 quad_perm:[0,0,0,0] row_mask:0xf bank_mask:0xf
	ds_read_b64 v[174:175], v125 offset:16512
	v_fmac_f32_dpp v117, -v171, v51 quad_perm:[0,0,0,0] row_mask:0xf bank_mask:0xf
	v_fmac_f32_dpp v118, -v170, v52 quad_perm:[1,1,1,1] row_mask:0xf bank_mask:0xf
	v_fmac_f32_dpp v119, -v171, v53 quad_perm:[1,1,1,1] row_mask:0xf bank_mask:0xf
	ds_read_b64 v[176:177], v125 offset:16544
	v_fmac_f32_dpp v116, -v170, v54 quad_perm:[2,2,2,2] row_mask:0xf bank_mask:0xf
	v_fmac_f32_dpp v117, -v171, v55 quad_perm:[2,2,2,2] row_mask:0xf bank_mask:0xf
	v_fmac_f32_dpp v118, -v170, v56 quad_perm:[3,3,3,3] row_mask:0xf bank_mask:0xf
	ds_read_b32 v214, v124 offset:240
	v_fmac_f32_dpp v119, -v171, v57 quad_perm:[3,3,3,3] row_mask:0xf bank_mask:0xf
	v_fmac_f32_dpp v116, -v186, v58 quad_perm:[0,0,0,0] row_mask:0xf bank_mask:0xf
	v_fmac_f32_dpp v117, -v187, v59 quad_perm:[0,0,0,0] row_mask:0xf bank_mask:0xf
	ds_read_u16_d16_hi v244, v123 offset:16320
	v_fmac_f32_dpp v118, -v186, v60 quad_perm:[1,1,1,1] row_mask:0xf bank_mask:0xf
	v_fmac_f32_dpp v119, -v187, v61 quad_perm:[1,1,1,1] row_mask:0xf bank_mask:0xf
	v_fmac_f32_dpp v116, -v186, v62 quad_perm:[2,2,2,2] row_mask:0xf bank_mask:0xf
	v_fmac_f32_dpp v117, -v187, v63 quad_perm:[2,2,2,2] row_mask:0xf bank_mask:0xf
	v_fmac_f32_dpp v118, -v186, v64 quad_perm:[3,3,3,3] row_mask:0xf bank_mask:0xf
	v_fmac_f32_dpp v119, -v187, v65 quad_perm:[3,3,3,3] row_mask:0xf bank_mask:0xf
	v_add_f32_e32 v121, v117, v116
	v_add_f32_e32 v122, v118, v119
	v_add_f32_e32 v66, v122, v121
	s_waitcnt lgkmcnt(15)
	v_fma_f32 v116, v211, v253, -v145
	v_fmac_f32_dpp v116, -v188, v42 quad_perm:[0,0,0,0] row_mask:0xf bank_mask:0xf
	v_mul_f32_dpp v117, -v189, v43 quad_perm:[0,0,0,0] row_mask:0xf bank_mask:0xf
	v_mul_f32_dpp v118, -v188, v44 quad_perm:[1,1,1,1] row_mask:0xf bank_mask:0xf
	ds_read_b64 v[178:179], v125 offset:16720
	v_mul_f32_dpp v119, -v189, v45 quad_perm:[1,1,1,1] row_mask:0xf bank_mask:0xf
	v_fmac_f32_dpp v116, -v188, v46 quad_perm:[2,2,2,2] row_mask:0xf bank_mask:0xf
	v_fmac_f32_dpp v117, -v189, v47 quad_perm:[2,2,2,2] row_mask:0xf bank_mask:0xf
	ds_read_b64 v[222:223], v125 offset:16752
	v_fmac_f32_dpp v118, -v188, v48 quad_perm:[3,3,3,3] row_mask:0xf bank_mask:0xf
	v_fmac_f32_dpp v119, -v189, v49 quad_perm:[3,3,3,3] row_mask:0xf bank_mask:0xf
	v_fmac_f32_dpp v116, -v190, v50 quad_perm:[0,0,0,0] row_mask:0xf bank_mask:0xf
	ds_read_b64 v[224:225], v125 offset:16784
	v_fmac_f32_dpp v117, -v191, v51 quad_perm:[0,0,0,0] row_mask:0xf bank_mask:0xf
	v_fmac_f32_dpp v118, -v190, v52 quad_perm:[1,1,1,1] row_mask:0xf bank_mask:0xf
	v_fmac_f32_dpp v119, -v191, v53 quad_perm:[1,1,1,1] row_mask:0xf bank_mask:0xf
	ds_read_b64 v[226:227], v125 offset:16816
	v_fmac_f32_dpp v116, -v190, v54 quad_perm:[2,2,2,2] row_mask:0xf bank_mask:0xf
	v_fmac_f32_dpp v117, -v191, v55 quad_perm:[2,2,2,2] row_mask:0xf bank_mask:0xf
	v_fmac_f32_dpp v118, -v190, v56 quad_perm:[3,3,3,3] row_mask:0xf bank_mask:0xf
	ds_read_b32 v215, v124 offset:244
	v_fmac_f32_dpp v119, -v191, v57 quad_perm:[3,3,3,3] row_mask:0xf bank_mask:0xf
	v_fmac_f32_dpp v116, -v192, v58 quad_perm:[0,0,0,0] row_mask:0xf bank_mask:0xf
	v_fmac_f32_dpp v117, -v193, v59 quad_perm:[0,0,0,0] row_mask:0xf bank_mask:0xf
	ds_read_u16_d16_hi v245, v123 offset:16592
	v_fmac_f32_dpp v118, -v192, v60 quad_perm:[1,1,1,1] row_mask:0xf bank_mask:0xf
	v_fmac_f32_dpp v119, -v193, v61 quad_perm:[1,1,1,1] row_mask:0xf bank_mask:0xf
	v_fmac_f32_dpp v116, -v192, v62 quad_perm:[2,2,2,2] row_mask:0xf bank_mask:0xf
	v_fmac_f32_dpp v117, -v193, v63 quad_perm:[2,2,2,2] row_mask:0xf bank_mask:0xf
	v_fmac_f32_dpp v118, -v192, v64 quad_perm:[3,3,3,3] row_mask:0xf bank_mask:0xf
	v_fmac_f32_dpp v119, -v193, v65 quad_perm:[3,3,3,3] row_mask:0xf bank_mask:0xf
	v_fmac_f32_dpp v116, -v194, v66 quad_perm:[0,0,0,0] row_mask:0xf bank_mask:0xf
	v_add_f32_e32 v121, v117, v116
	v_add_f32_e32 v122, v118, v119
	v_add_f32_e32 v67, v122, v121
	s_waitcnt lgkmcnt(15)
; __device__ __forceinline__ float bf2f(bf16 v) { return __uint_as_float(((unsigned)v) << 16); }
; #define GDN_LOADROW(buf, rr_, i_) do { _Pragma("unroll") for (int j4 = 0; j4 < ((i_) + 3) / 4; ++j4) buf[j4] = *(const f32x4*)(Lm + (i_) * GP_LSTR + 4 * j4); rr_ = bf2f(*(const bf16*)(xsrc + (i_) * GP_STR * 2)) * scl[i_]; } while (0)
; template <int STRIP> __device__ __forceinline__ void ph_gdn_prep_fast(const bf16* __restrict__ proj, const float* __restrict__ small, const float* __restrict__ conv_w, const float* __restrict__ a_log, const float* __restrict__ dt_bias, ...
;     ...
;             rA = bf2f(*(const bf16*)xsrc) * scl[0];
;     ...
; #pragma unroll
;             for (int i = 0; i < 64; i += 2) {
;                 GDN_LOADROW(bB, rB, i + 1);
;                 GDN_ROW(bA, rA, i);
;                 if (i + 2 < 64) GDN_LOADROW(bA, rA, i + 2);
;                 GDN_ROW(bB, rB, i + 1);
;             }
	v_fma_f32 v116, v212, v126, -v146
	v_fmac_f32_dpp v116, -v196, v42 quad_perm:[0,0,0,0] row_mask:0xf bank_mask:0xf
	v_mul_f32_dpp v117, -v197, v43 quad_perm:[0,0,0,0] row_mask:0xf bank_mask:0xf
	ds_read_b64 v[228:229], v125 offset:16992
	v_mul_f32_dpp v118, -v196, v44 quad_perm:[1,1,1,1] row_mask:0xf bank_mask:0xf
	v_mul_f32_dpp v119, -v197, v45 quad_perm:[1,1,1,1] row_mask:0xf bank_mask:0xf
	v_fmac_f32_dpp v116, -v196, v46 quad_perm:[2,2,2,2] row_mask:0xf bank_mask:0xf
	ds_read_b64 v[170:171], v125 offset:17024
	v_fmac_f32_dpp v117, -v197, v47 quad_perm:[2,2,2,2] row_mask:0xf bank_mask:0xf
	v_fmac_f32_dpp v118, -v196, v48 quad_perm:[3,3,3,3] row_mask:0xf bank_mask:0xf
	v_fmac_f32_dpp v119, -v197, v49 quad_perm:[3,3,3,3] row_mask:0xf bank_mask:0xf
	ds_read_b64 v[186:187], v125 offset:17056
	v_fmac_f32_dpp v116, -v198, v50 quad_perm:[0,0,0,0] row_mask:0xf bank_mask:0xf
	v_fmac_f32_dpp v117, -v199, v51 quad_perm:[0,0,0,0] row_mask:0xf bank_mask:0xf
	v_fmac_f32_dpp v118, -v198, v52 quad_perm:[1,1,1,1] row_mask:0xf bank_mask:0xf
	ds_read_b64 v[188:189], v125 offset:17088
	v_fmac_f32_dpp v119, -v199, v53 quad_perm:[1,1,1,1] row_mask:0xf bank_mask:0xf
	v_fmac_f32_dpp v116, -v198, v54 quad_perm:[2,2,2,2] row_mask:0xf bank_mask:0xf
	v_fmac_f32_dpp v117, -v199, v55 quad_perm:[2,2,2,2] row_mask:0xf bank_mask:0xf
	ds_read_b32 v216, v124 offset:248
	v_fmac_f32_dpp v118, -v198, v56 quad_perm:[3,3,3,3] row_mask:0xf bank_mask:0xf
	v_fmac_f32_dpp v119, -v199, v57 quad_perm:[3,3,3,3] row_mask:0xf bank_mask:0xf
	v_fmac_f32_dpp v116, -v200, v58 quad_perm:[0,0,0,0] row_mask:0xf bank_mask:0xf
	ds_read_u16_d16_hi v246, v123 offset:16864
	v_fmac_f32_dpp v117, -v201, v59 quad_perm:[0,0,0,0] row_mask:0xf bank_mask:0xf
	v_fmac_f32_dpp v118, -v200, v60 quad_perm:[1,1,1,1] row_mask:0xf bank_mask:0xf
	v_fmac_f32_dpp v119, -v201, v61 quad_perm:[1,1,1,1] row_mask:0xf bank_mask:0xf
	v_fmac_f32_dpp v116, -v200, v62 quad_perm:[2,2,2,2] row_mask:0xf bank_mask:0xf
	v_fmac_f32_dpp v117, -v201, v63 quad_perm:[2,2,2,2] row_mask:0xf bank_mask:0xf
	v_fmac_f32_dpp v118, -v200, v64 quad_perm:[3,3,3,3] row_mask:0xf bank_mask:0xf
	v_fmac_f32_dpp v119, -v201, v65 quad_perm:[3,3,3,3] row_mask:0xf bank_mask:0xf
	v_fmac_f32_dpp v116, -v202, v66 quad_perm:[0,0,0,0] row_mask:0xf bank_mask:0xf
	v_fmac_f32_dpp v117, -v203, v67 quad_perm:[0,0,0,0] row_mask:0xf bank_mask:0xf
	v_add_f32_e32 v121, v117, v116
	v_add_f32_e32 v122, v118, v119
	v_add_f32_e32 v68, v122, v121
	s_waitcnt lgkmcnt(15)
	v_fma_f32 v116, v213, v127, -v147
	v_fmac_f32_dpp v116, -v204, v42 quad_perm:[0,0,0,0] row_mask:0xf bank_mask:0xf
	v_mul_f32_dpp v117, -v205, v43 quad_perm:[0,0,0,0] row_mask:0xf bank_mask:0xf
	v_mul_f32_dpp v118, -v204, v44 quad_perm:[1,1,1,1] row_mask:0xf bank_mask:0xf
	ds_read_b64 v[190:191], v125 offset:17264
	v_mul_f32_dpp v119, -v205, v45 quad_perm:[1,1,1,1] row_mask:0xf bank_mask:0xf
	v_fmac_f32_dpp v116, -v204, v46 quad_perm:[2,2,2,2] row_mask:0xf bank_mask:0xf
	v_fmac_f32_dpp v117, -v205, v47 quad_perm:[2,2,2,2] row_mask:0xf bank_mask:0xf
	ds_read_b64 v[192:193], v125 offset:17296
	v_fmac_f32_dpp v118, -v204, v48 quad_perm:[3,3,3,3] row_mask:0xf bank_mask:0xf
	v_fmac_f32_dpp v119, -v205, v49 quad_perm:[3,3,3,3] row_mask:0xf bank_mask:0xf
	v_fmac_f32_dpp v116, -v206, v50 quad_perm:[0,0,0,0] row_mask:0xf bank_mask:0xf
	ds_read_b64 v[194:195], v125 offset:17328
	v_fmac_f32_dpp v117, -v207, v51 quad_perm:[0,0,0,0] row_mask:0xf bank_mask:0xf
	v_fmac_f32_dpp v118, -v206, v52 quad_perm:[1,1,1,1] row_mask:0xf bank_mask:0xf
	v_fmac_f32_dpp v119, -v207, v53 quad_perm:[1,1,1,1] row_mask:0xf bank_mask:0xf
	ds_read_b64 v[196:197], v125 offset:17360
	v_fmac_f32_dpp v116, -v206, v54 quad_perm:[2,2,2,2] row_mask:0xf bank_mask:0xf
	v_fmac_f32_dpp v117, -v207, v55 quad_perm:[2,2,2,2] row_mask:0xf bank_mask:0xf
	v_fmac_f32_dpp v118, -v206, v56 quad_perm:[3,3,3,3] row_mask:0xf bank_mask:0xf
	ds_read_b32 v217, v124 offset:252
	v_fmac_f32_dpp v119, -v207, v57 quad_perm:[3,3,3,3] row_mask:0xf bank_mask:0xf
	v_fmac_f32_dpp v116, -v164, v58 quad_perm:[0,0,0,0] row_mask:0xf bank_mask:0xf
	v_fmac_f32_dpp v117, -v165, v59 quad_perm:[0,0,0,0] row_mask:0xf bank_mask:0xf
	ds_read_u16_d16_hi v247, v123 offset:17136
	v_fmac_f32_dpp v118, -v164, v60 quad_perm:[1,1,1,1] row_mask:0xf bank_mask:0xf
	v_fmac_f32_dpp v119, -v165, v61 quad_perm:[1,1,1,1] row_mask:0xf bank_mask:0xf
	v_fmac_f32_dpp v116, -v164, v62 quad_perm:[2,2,2,2] row_mask:0xf bank_mask:0xf
	v_fmac_f32_dpp v117, -v165, v63 quad_perm:[2,2,2,2] row_mask:0xf bank_mask:0xf
	v_fmac_f32_dpp v118, -v164, v64 quad_perm:[3,3,3,3] row_mask:0xf bank_mask:0xf
	v_fmac_f32_dpp v119, -v165, v65 quad_perm:[3,3,3,3] row_mask:0xf bank_mask:0xf
	v_fmac_f32_dpp v116, -v166, v66 quad_perm:[0,0,0,0] row_mask:0xf bank_mask:0xf
	v_fmac_f32_dpp v117, -v167, v67 quad_perm:[0,0,0,0] row_mask:0xf bank_mask:0xf
	v_fmac_f32_dpp v118, -v166, v68 quad_perm:[1,1,1,1] row_mask:0xf bank_mask:0xf
	v_add_f32_e32 v121, v117, v116
	v_add_f32_e32 v122, v118, v119
	v_add_f32_e32 v69, v122, v121
	s_waitcnt lgkmcnt(15)
; #define GDN_LOADROW(buf, rr_, i_) do { _Pragma("unroll") for (int j4 = 0; j4 < ((i_) + 3) / 4; ++j4) buf[j4] = *(const f32x4*)(Lm + (i_) * GP_LSTR + 4 * j4); rr_ = bf2f(*(const bf16*)(xsrc + (i_) * GP_STR * 2)) * scl[i_]; } while (0)
; template <int STRIP> __device__ __forceinline__ void ph_gdn_prep_fast(const bf16* __restrict__ proj, const float* __restrict__ small, const float* __restrict__ conv_w, const float* __restrict__ a_log, const float* __restrict__ dt_bias, ...
;     ...
; #pragma unroll
;             for (int i = 0; i < 64; i += 2) {
;                 GDN_LOADROW(bB, rB, i + 1);
;                 GDN_ROW(bA, rA, i);
;                 if (i + 2 < 64) GDN_LOADROW(bA, rA, i + 2);
;                 GDN_ROW(bB, rB, i + 1);
;             }
	v_fma_f32 v116, v214, v244, -v160
	v_fmac_f32_dpp v116, -v168, v42 quad_perm:[0,0,0,0] row_mask:0xf bank_mask:0xf
	v_mul_f32_dpp v117, -v169, v43 quad_perm:[0,0,0,0] row_mask:0xf bank_mask:0xf
	v_mul_f32_dpp v118, -v168, v44 quad_perm:[1,1,1,1] row_mask:0xf bank_mask:0xf
	v_mul_f32_dpp v119, -v169, v45 quad_perm:[1,1,1,1] row_mask:0xf bank_mask:0xf
	v_fmac_f32_dpp v116, -v168, v46 quad_perm:[2,2,2,2] row_mask:0xf bank_mask:0xf
	v_fmac_f32_dpp v117, -v169, v47 quad_perm:[2,2,2,2] row_mask:0xf bank_mask:0xf
	v_fmac_f32_dpp v118, -v168, v48 quad_perm:[3,3,3,3] row_mask:0xf bank_mask:0xf
	v_fmac_f32_dpp v119, -v169, v49 quad_perm:[3,3,3,3] row_mask:0xf bank_mask:0xf
	v_fmac_f32_dpp v116, -v172, v50 quad_perm:[0,0,0,0] row_mask:0xf bank_mask:0xf
	v_fmac_f32_dpp v117, -v173, v51 quad_perm:[0,0,0,0] row_mask:0xf bank_mask:0xf
	v_fmac_f32_dpp v118, -v172, v52 quad_perm:[1,1,1,1] row_mask:0xf bank_mask:0xf
	v_fmac_f32_dpp v119, -v173, v53 quad_perm:[1,1,1,1] row_mask:0xf bank_mask:0xf
	v_fmac_f32_dpp v116, -v172, v54 quad_perm:[2,2,2,2] row_mask:0xf bank_mask:0xf
	v_fmac_f32_dpp v117, -v173, v55 quad_perm:[2,2,2,2] row_mask:0xf bank_mask:0xf
	v_fmac_f32_dpp v118, -v172, v56 quad_perm:[3,3,3,3] row_mask:0xf bank_mask:0xf
	v_fmac_f32_dpp v119, -v173, v57 quad_perm:[3,3,3,3] row_mask:0xf bank_mask:0xf
	v_fmac_f32_dpp v116, -v174, v58 quad_perm:[0,0,0,0] row_mask:0xf bank_mask:0xf
	v_fmac_f32_dpp v117, -v175, v59 quad_perm:[0,0,0,0] row_mask:0xf bank_mask:0xf
	v_fmac_f32_dpp v118, -v174, v60 quad_perm:[1,1,1,1] row_mask:0xf bank_mask:0xf
	v_fmac_f32_dpp v119, -v175, v61 quad_perm:[1,1,1,1] row_mask:0xf bank_mask:0xf
	v_fmac_f32_dpp v116, -v174, v62 quad_perm:[2,2,2,2] row_mask:0xf bank_mask:0xf
	v_fmac_f32_dpp v117, -v175, v63 quad_perm:[2,2,2,2] row_mask:0xf bank_mask:0xf
	v_fmac_f32_dpp v118, -v174, v64 quad_perm:[3,3,3,3] row_mask:0xf bank_mask:0xf
	v_fmac_f32_dpp v119, -v175, v65 quad_perm:[3,3,3,3] row_mask:0xf bank_mask:0xf
	v_fmac_f32_dpp v116, -v176, v66 quad_perm:[0,0,0,0] row_mask:0xf bank_mask:0xf
	v_fmac_f32_dpp v117, -v177, v67 quad_perm:[0,0,0,0] row_mask:0xf bank_mask:0xf
	v_fmac_f32_dpp v118, -v176, v68 quad_perm:[1,1,1,1] row_mask:0xf bank_mask:0xf
	v_fmac_f32_dpp v119, -v177, v69 quad_perm:[1,1,1,1] row_mask:0xf bank_mask:0xf
	v_add_f32_e32 v121, v117, v116
	v_add_f32_e32 v122, v118, v119
	v_add_f32_e32 v70, v122, v121
	s_waitcnt lgkmcnt(12)
	v_fma_f32 v116, v215, v245, -v161
	v_fmac_f32_dpp v116, -v178, v42 quad_perm:[0,0,0,0] row_mask:0xf bank_mask:0xf
	v_mul_f32_dpp v117, -v179, v43 quad_perm:[0,0,0,0] row_mask:0xf bank_mask:0xf
	v_mul_f32_dpp v118, -v178, v44 quad_perm:[1,1,1,1] row_mask:0xf bank_mask:0xf
	v_mul_f32_dpp v119, -v179, v45 quad_perm:[1,1,1,1] row_mask:0xf bank_mask:0xf
	v_fmac_f32_dpp v116, -v178, v46 quad_perm:[2,2,2,2] row_mask:0xf bank_mask:0xf
	v_fmac_f32_dpp v117, -v179, v47 quad_perm:[2,2,2,2] row_mask:0xf bank_mask:0xf
	v_fmac_f32_dpp v118, -v178, v48 quad_perm:[3,3,3,3] row_mask:0xf bank_mask:0xf
	v_fmac_f32_dpp v119, -v179, v49 quad_perm:[3,3,3,3] row_mask:0xf bank_mask:0xf
	v_fmac_f32_dpp v116, -v222, v50 quad_perm:[0,0,0,0] row_mask:0xf bank_mask:0xf
	v_fmac_f32_dpp v117, -v223, v51 quad_perm:[0,0,0,0] row_mask:0xf bank_mask:0xf
	v_fmac_f32_dpp v118, -v222, v52 quad_perm:[1,1,1,1] row_mask:0xf bank_mask:0xf
	v_fmac_f32_dpp v119, -v223, v53 quad_perm:[1,1,1,1] row_mask:0xf bank_mask:0xf
	v_fmac_f32_dpp v116, -v222, v54 quad_perm:[2,2,2,2] row_mask:0xf bank_mask:0xf
	v_fmac_f32_dpp v117, -v223, v55 quad_perm:[2,2,2,2] row_mask:0xf bank_mask:0xf
	v_fmac_f32_dpp v118, -v222, v56 quad_perm:[3,3,3,3] row_mask:0xf bank_mask:0xf
	v_fmac_f32_dpp v119, -v223, v57 quad_perm:[3,3,3,3] row_mask:0xf bank_mask:0xf
	v_fmac_f32_dpp v116, -v224, v58 quad_perm:[0,0,0,0] row_mask:0xf bank_mask:0xf
	v_fmac_f32_dpp v117, -v225, v59 quad_perm:[0,0,0,0] row_mask:0xf bank_mask:0xf
	v_fmac_f32_dpp v118, -v224, v60 quad_perm:[1,1,1,1] row_mask:0xf bank_mask:0xf
	v_fmac_f32_dpp v119, -v225, v61 quad_perm:[1,1,1,1] row_mask:0xf bank_mask:0xf
	v_fmac_f32_dpp v116, -v224, v62 quad_perm:[2,2,2,2] row_mask:0xf bank_mask:0xf
	v_fmac_f32_dpp v117, -v225, v63 quad_perm:[2,2,2,2] row_mask:0xf bank_mask:0xf
	v_fmac_f32_dpp v118, -v224, v64 quad_perm:[3,3,3,3] row_mask:0xf bank_mask:0xf
	v_fmac_f32_dpp v119, -v225, v65 quad_perm:[3,3,3,3] row_mask:0xf bank_mask:0xf
	v_fmac_f32_dpp v116, -v226, v66 quad_perm:[0,0,0,0] row_mask:0xf bank_mask:0xf
	v_fmac_f32_dpp v117, -v227, v67 quad_perm:[0,0,0,0] row_mask:0xf bank_mask:0xf
	v_fmac_f32_dpp v118, -v226, v68 quad_perm:[1,1,1,1] row_mask:0xf bank_mask:0xf
	v_fmac_f32_dpp v119, -v227, v69 quad_perm:[1,1,1,1] row_mask:0xf bank_mask:0xf
	v_fmac_f32_dpp v116, -v226, v70 quad_perm:[2,2,2,2] row_mask:0xf bank_mask:0xf
	v_add_f32_e32 v121, v117, v116
	v_add_f32_e32 v122, v118, v119
	v_add_f32_e32 v71, v122, v121
	s_waitcnt lgkmcnt(6)
; #define GDN_LOADROW(buf, rr_, i_) do { _Pragma("unroll") for (int j4 = 0; j4 < ((i_) + 3) / 4; ++j4) buf[j4] = *(const f32x4*)(Lm + (i_) * GP_LSTR + 4 * j4); rr_ = bf2f(*(const bf16*)(xsrc + (i_) * GP_STR * 2)) * scl[i_]; } while (0)
; template <int STRIP> __device__ __forceinline__ void ph_gdn_prep_fast(const bf16* __restrict__ proj, const float* __restrict__ small, const float* __restrict__ conv_w, const float* __restrict__ a_log, const float* __restrict__ dt_bias, ...
;     ...
; #pragma unroll
;             for (int i = 0; i < 64; i += 2) {
;                 GDN_LOADROW(bB, rB, i + 1);
;                 GDN_ROW(bA, rA, i);
;                 if (i + 2 < 64) GDN_LOADROW(bA, rA, i + 2);
;                 GDN_ROW(bB, rB, i + 1);
;             }
;     ...
;             if (STRIP == 3) { if (U[63] == 12345.678f) EGL[ci] = U[5]; } else
;             if (!isw) { const int v = cc >> 4, c15 = cc & 15; bf16* dst = UF + ((size_t)ci * 8 + v) * 64 * 16;
	v_fma_f32 v116, v216, v246, -v162
	v_fmac_f32_dpp v116, -v228, v42 quad_perm:[0,0,0,0] row_mask:0xf bank_mask:0xf
	v_mul_f32_dpp v117, -v229, v43 quad_perm:[0,0,0,0] row_mask:0xf bank_mask:0xf
	v_mul_f32_dpp v118, -v228, v44 quad_perm:[1,1,1,1] row_mask:0xf bank_mask:0xf
	v_mul_f32_dpp v119, -v229, v45 quad_perm:[1,1,1,1] row_mask:0xf bank_mask:0xf
	v_fmac_f32_dpp v116, -v228, v46 quad_perm:[2,2,2,2] row_mask:0xf bank_mask:0xf
	v_fmac_f32_dpp v117, -v229, v47 quad_perm:[2,2,2,2] row_mask:0xf bank_mask:0xf
	v_fmac_f32_dpp v118, -v228, v48 quad_perm:[3,3,3,3] row_mask:0xf bank_mask:0xf
	v_fmac_f32_dpp v119, -v229, v49 quad_perm:[3,3,3,3] row_mask:0xf bank_mask:0xf
	v_fmac_f32_dpp v116, -v170, v50 quad_perm:[0,0,0,0] row_mask:0xf bank_mask:0xf
	v_fmac_f32_dpp v117, -v171, v51 quad_perm:[0,0,0,0] row_mask:0xf bank_mask:0xf
	v_fmac_f32_dpp v118, -v170, v52 quad_perm:[1,1,1,1] row_mask:0xf bank_mask:0xf
	v_fmac_f32_dpp v119, -v171, v53 quad_perm:[1,1,1,1] row_mask:0xf bank_mask:0xf
	v_fmac_f32_dpp v116, -v170, v54 quad_perm:[2,2,2,2] row_mask:0xf bank_mask:0xf
	v_fmac_f32_dpp v117, -v171, v55 quad_perm:[2,2,2,2] row_mask:0xf bank_mask:0xf
	v_fmac_f32_dpp v118, -v170, v56 quad_perm:[3,3,3,3] row_mask:0xf bank_mask:0xf
	v_fmac_f32_dpp v119, -v171, v57 quad_perm:[3,3,3,3] row_mask:0xf bank_mask:0xf
	v_fmac_f32_dpp v116, -v186, v58 quad_perm:[0,0,0,0] row_mask:0xf bank_mask:0xf
	v_fmac_f32_dpp v117, -v187, v59 quad_perm:[0,0,0,0] row_mask:0xf bank_mask:0xf
	v_fmac_f32_dpp v118, -v186, v60 quad_perm:[1,1,1,1] row_mask:0xf bank_mask:0xf
	v_fmac_f32_dpp v119, -v187, v61 quad_perm:[1,1,1,1] row_mask:0xf bank_mask:0xf
	v_fmac_f32_dpp v116, -v186, v62 quad_perm:[2,2,2,2] row_mask:0xf bank_mask:0xf
	v_fmac_f32_dpp v117, -v187, v63 quad_perm:[2,2,2,2] row_mask:0xf bank_mask:0xf
	v_fmac_f32_dpp v118, -v186, v64 quad_perm:[3,3,3,3] row_mask:0xf bank_mask:0xf
	v_fmac_f32_dpp v119, -v187, v65 quad_perm:[3,3,3,3] row_mask:0xf bank_mask:0xf
	v_fmac_f32_dpp v116, -v188, v66 quad_perm:[0,0,0,0] row_mask:0xf bank_mask:0xf
	v_fmac_f32_dpp v117, -v189, v67 quad_perm:[0,0,0,0] row_mask:0xf bank_mask:0xf
	v_fmac_f32_dpp v118, -v188, v68 quad_perm:[1,1,1,1] row_mask:0xf bank_mask:0xf
	v_fmac_f32_dpp v119, -v189, v69 quad_perm:[1,1,1,1] row_mask:0xf bank_mask:0xf
	v_fmac_f32_dpp v116, -v188, v70 quad_perm:[2,2,2,2] row_mask:0xf bank_mask:0xf
	v_fmac_f32_dpp v117, -v189, v71 quad_perm:[2,2,2,2] row_mask:0xf bank_mask:0xf
	v_add_f32_e32 v121, v117, v116
	v_add_f32_e32 v122, v118, v119
	v_add_f32_e32 v26, v122, v121
	s_waitcnt lgkmcnt(0)
	v_fma_f32 v116, v217, v247, -v163
	v_fmac_f32_dpp v116, -v190, v42 quad_perm:[0,0,0,0] row_mask:0xf bank_mask:0xf
	v_mul_f32_dpp v117, -v191, v43 quad_perm:[0,0,0,0] row_mask:0xf bank_mask:0xf
	v_mul_f32_dpp v118, -v190, v44 quad_perm:[1,1,1,1] row_mask:0xf bank_mask:0xf
	v_mul_f32_dpp v119, -v191, v45 quad_perm:[1,1,1,1] row_mask:0xf bank_mask:0xf
	v_fmac_f32_dpp v116, -v190, v46 quad_perm:[2,2,2,2] row_mask:0xf bank_mask:0xf
	v_fmac_f32_dpp v117, -v191, v47 quad_perm:[2,2,2,2] row_mask:0xf bank_mask:0xf
	v_fmac_f32_dpp v118, -v190, v48 quad_perm:[3,3,3,3] row_mask:0xf bank_mask:0xf
	v_fmac_f32_dpp v119, -v191, v49 quad_perm:[3,3,3,3] row_mask:0xf bank_mask:0xf
	v_fmac_f32_dpp v116, -v192, v50 quad_perm:[0,0,0,0] row_mask:0xf bank_mask:0xf
	v_fmac_f32_dpp v117, -v193, v51 quad_perm:[0,0,0,0] row_mask:0xf bank_mask:0xf
	v_fmac_f32_dpp v118, -v192, v52 quad_perm:[1,1,1,1] row_mask:0xf bank_mask:0xf
	v_fmac_f32_dpp v119, -v193, v53 quad_perm:[1,1,1,1] row_mask:0xf bank_mask:0xf
	v_fmac_f32_dpp v116, -v192, v54 quad_perm:[2,2,2,2] row_mask:0xf bank_mask:0xf
	v_fmac_f32_dpp v117, -v193, v55 quad_perm:[2,2,2,2] row_mask:0xf bank_mask:0xf
	v_fmac_f32_dpp v118, -v192, v56 quad_perm:[3,3,3,3] row_mask:0xf bank_mask:0xf
	v_fmac_f32_dpp v119, -v193, v57 quad_perm:[3,3,3,3] row_mask:0xf bank_mask:0xf
	v_fmac_f32_dpp v116, -v194, v58 quad_perm:[0,0,0,0] row_mask:0xf bank_mask:0xf
	v_fmac_f32_dpp v117, -v195, v59 quad_perm:[0,0,0,0] row_mask:0xf bank_mask:0xf
	v_fmac_f32_dpp v118, -v194, v60 quad_perm:[1,1,1,1] row_mask:0xf bank_mask:0xf
	v_fmac_f32_dpp v119, -v195, v61 quad_perm:[1,1,1,1] row_mask:0xf bank_mask:0xf
	v_fmac_f32_dpp v116, -v194, v62 quad_perm:[2,2,2,2] row_mask:0xf bank_mask:0xf
	v_fmac_f32_dpp v117, -v195, v63 quad_perm:[2,2,2,2] row_mask:0xf bank_mask:0xf
	v_fmac_f32_dpp v118, -v194, v64 quad_perm:[3,3,3,3] row_mask:0xf bank_mask:0xf
	v_fmac_f32_dpp v119, -v195, v65 quad_perm:[3,3,3,3] row_mask:0xf bank_mask:0xf
	v_fmac_f32_dpp v116, -v196, v66 quad_perm:[0,0,0,0] row_mask:0xf bank_mask:0xf
	v_fmac_f32_dpp v117, -v197, v67 quad_perm:[0,0,0,0] row_mask:0xf bank_mask:0xf
	v_fmac_f32_dpp v118, -v196, v68 quad_perm:[1,1,1,1] row_mask:0xf bank_mask:0xf
	v_fmac_f32_dpp v119, -v197, v69 quad_perm:[1,1,1,1] row_mask:0xf bank_mask:0xf
	v_fmac_f32_dpp v116, -v196, v70 quad_perm:[2,2,2,2] row_mask:0xf bank_mask:0xf
	v_fmac_f32_dpp v117, -v197, v71 quad_perm:[2,2,2,2] row_mask:0xf bank_mask:0xf
	v_fmac_f32_dpp v118, -v196, v26 quad_perm:[3,3,3,3] row_mask:0xf bank_mask:0xf
	v_add_f32_e32 v121, v117, v116
	v_add_f32_e32 v122, v118, v119
	v_add_f32_e32 v72, v122, v121
	v_add_u32_e32 v8, v79, v8
	v_ashrrev_i32_e32 v9, 31, v8
	v_lshlrev_b64 v[8:9], 14, v[8:9]
	v_lshlrev_b32_e32 v73, 4, v78
	s_and_saveexec_b64 s[0:1], vcc
	s_xor_b64 s[0:1], exec, s[0:1]
	s_cbranch_execz .LBB0_1305
; __device__ __forceinline__ bf16 f2bf(float f) { return (bf16)(pk2(f, 0.f) & 0xffffu); }
; __device__ __forceinline__ int gperm(int x) { return (x & ~31) | ((x & 12) << 1) | ((x & 16) >> 2) | (x & 3); }
; template <int STRIP> __device__ __forceinline__ void ph_gdn_prep_fast(const bf16* __restrict__ proj, const float* __restrict__ small, const float* __restrict__ conv_w, const float* __restrict__ a_log, const float* __restrict__ dt_bias, ...
;     ...
;             else { bf16* dst = WP + (size_t)ci * 64 * 128 + gperm(cc);
; #pragma unroll
;                 for (int i = 0; i < 64; ++i) __builtin_nontemporal_store(f2bf(U[i]), dst + i * 128); }
	v_and_b32_e32 v2, 24, v18
	v_lshrrev_b32_e32 v18, 2, v78
	v_and_b32_e32 v18, 4, v18
	v_and_b32_e32 v73, 0x63, v78
	v_or3_b32 v2, v18, v73, v2
	v_lshl_add_u64 v[74:75], s[34:35], 0, v[8:9]
	v_lshlrev_b32_e32 v2, 1, v2
	v_lshl_add_u64 v[74:75], v[74:75], 0, v[2:3]
	v_cvt_pk_bf16_f32 v2, v4, s0
	global_store_short v[74:75], v2, off nt
	v_cvt_pk_bf16_f32 v2, v5, s0
	global_store_short v[74:75], v2, off offset:256 nt
	v_cvt_pk_bf16_f32 v2, v6, s0
	global_store_short v[74:75], v2, off offset:512 nt
	v_cvt_pk_bf16_f32 v2, v12, s0
	global_store_short v[74:75], v2, off offset:768 nt
	v_cvt_pk_bf16_f32 v2, v7, s0
	global_store_short v[74:75], v2, off offset:1024 nt
	v_cvt_pk_bf16_f32 v2, v13, s0
	global_store_short v[74:75], v2, off offset:1280 nt
	v_cvt_pk_bf16_f32 v2, v14, s0
	global_store_short v[74:75], v2, off offset:1536 nt
	v_cvt_pk_bf16_f32 v2, v15, s0
	global_store_short v[74:75], v2, off offset:1792 nt
	v_cvt_pk_bf16_f32 v2, v16, s0
	global_store_short v[74:75], v2, off offset:2048 nt
	v_cvt_pk_bf16_f32 v2, v17, s0
	global_store_short v[74:75], v2, off offset:2304 nt
	v_cvt_pk_bf16_f32 v2, v19, s0
	global_store_short v[74:75], v2, off offset:2560 nt
	v_cvt_pk_bf16_f32 v2, v20, s0
	global_store_short v[74:75], v2, off offset:2816 nt
	v_cvt_pk_bf16_f32 v2, v21, s0
	global_store_short v[74:75], v2, off offset:3072 nt
	v_cvt_pk_bf16_f32 v2, v22, s0
	v_add_co_u32_e32 v4, vcc, s79, v74
	global_store_short v[74:75], v2, off offset:3328 nt
	v_cvt_pk_bf16_f32 v2, v23, s0
	v_addc_co_u32_e32 v5, vcc, 0, v75, vcc
	global_store_short v[74:75], v2, off offset:3584 nt
	v_cvt_pk_bf16_f32 v2, v24, s0
	v_add_co_u32_e32 v6, vcc, s76, v74
	global_store_short v[74:75], v2, off offset:3840 nt
	v_cvt_pk_bf16_f32 v2, v25, s0
	v_addc_co_u32_e32 v7, vcc, 0, v75, vcc
	global_store_short v[6:7], v2, off offset:-4096 nt
	v_cvt_pk_bf16_f32 v2, v27, s0
	global_store_short v[4:5], v2, off offset:256 nt
	v_cvt_pk_bf16_f32 v2, v28, s0
	global_store_short v[4:5], v2, off offset:512 nt
	v_cvt_pk_bf16_f32 v2, v29, s0
	global_store_short v[4:5], v2, off offset:768 nt
	v_cvt_pk_bf16_f32 v2, v30, s0
	global_store_short v[4:5], v2, off offset:1024 nt
	v_cvt_pk_bf16_f32 v2, v31, s0
	global_store_short v[4:5], v2, off offset:1280 nt
	v_cvt_pk_bf16_f32 v2, v32, s0
	global_store_short v[4:5], v2, off offset:1536 nt
	v_cvt_pk_bf16_f32 v2, v33, s0
	global_store_short v[4:5], v2, off offset:1792 nt
	v_cvt_pk_bf16_f32 v2, v34, s0
	global_store_short v[4:5], v2, off offset:2048 nt
	v_cvt_pk_bf16_f32 v2, v35, s0
	global_store_short v[4:5], v2, off offset:2304 nt
	v_cvt_pk_bf16_f32 v2, v36, s0
	global_store_short v[4:5], v2, off offset:2560 nt
	v_cvt_pk_bf16_f32 v2, v37, s0
	global_store_short v[4:5], v2, off offset:2816 nt
	v_cvt_pk_bf16_f32 v2, v38, s0
	global_store_short v[4:5], v2, off offset:3072 nt
	v_cvt_pk_bf16_f32 v2, v39, s0
	global_store_short v[4:5], v2, off offset:3328 nt
	v_cvt_pk_bf16_f32 v2, v40, s0
	global_store_short v[4:5], v2, off offset:3584 nt
	v_cvt_pk_bf16_f32 v2, v41, s0
	global_store_short v[4:5], v2, off offset:3840 nt
	v_cvt_pk_bf16_f32 v2, v42, s0
	global_store_short v[6:7], v2, off nt
	v_cvt_pk_bf16_f32 v2, v43, s0
	global_store_short v[6:7], v2, off offset:256 nt
	v_cvt_pk_bf16_f32 v2, v44, s0
	global_store_short v[6:7], v2, off offset:512 nt
	v_cvt_pk_bf16_f32 v2, v45, s0
	global_store_short v[6:7], v2, off offset:768 nt
	v_cvt_pk_bf16_f32 v2, v46, s0
	global_store_short v[6:7], v2, off offset:1024 nt
	v_cvt_pk_bf16_f32 v2, v47, s0
	global_store_short v[6:7], v2, off offset:1280 nt
	v_cvt_pk_bf16_f32 v2, v48, s0
	global_store_short v[6:7], v2, off offset:1536 nt
	v_cvt_pk_bf16_f32 v2, v49, s0
	global_store_short v[6:7], v2, off offset:1792 nt
	v_cvt_pk_bf16_f32 v2, v50, s0
	global_store_short v[6:7], v2, off offset:2048 nt
	v_cvt_pk_bf16_f32 v2, v51, s0
	global_store_short v[6:7], v2, off offset:2304 nt
	v_cvt_pk_bf16_f32 v2, v52, s0
	global_store_short v[6:7], v2, off offset:2560 nt
	v_cvt_pk_bf16_f32 v2, v53, s0
	global_store_short v[6:7], v2, off offset:2816 nt
	v_cvt_pk_bf16_f32 v2, v54, s0
	global_store_short v[6:7], v2, off offset:3072 nt
	v_cvt_pk_bf16_f32 v2, v55, s0
	global_store_short v[6:7], v2, off offset:3328 nt
	v_cvt_pk_bf16_f32 v2, v56, s0
	s_movk_i32 s2, 0x3000
	global_store_short v[6:7], v2, off offset:3584 nt
	v_cvt_pk_bf16_f32 v2, v57, s0
	v_add_co_u32_e32 v4, vcc, s2, v74
	global_store_short v[6:7], v2, off offset:3840 nt
	v_cvt_pk_bf16_f32 v2, v58, s0
	v_addc_co_u32_e32 v5, vcc, 0, v75, vcc
	global_store_short v[4:5], v2, off nt
	v_cvt_pk_bf16_f32 v2, v59, s0
	global_store_short v[4:5], v2, off offset:256 nt
	v_cvt_pk_bf16_f32 v2, v60, s0
	global_store_short v[4:5], v2, off offset:512 nt
	v_cvt_pk_bf16_f32 v2, v61, s0
	global_store_short v[4:5], v2, off offset:768 nt
	v_cvt_pk_bf16_f32 v2, v62, s0
	global_store_short v[4:5], v2, off offset:1024 nt
	v_cvt_pk_bf16_f32 v2, v63, s0
	global_store_short v[4:5], v2, off offset:1280 nt
	v_cvt_pk_bf16_f32 v2, v64, s0
	global_store_short v[4:5], v2, off offset:1536 nt
	v_cvt_pk_bf16_f32 v2, v65, s0
	global_store_short v[4:5], v2, off offset:1792 nt
	v_cvt_pk_bf16_f32 v2, v66, s0
	global_store_short v[4:5], v2, off offset:2048 nt
	v_cvt_pk_bf16_f32 v2, v67, s0
	global_store_short v[4:5], v2, off offset:2304 nt
	v_cvt_pk_bf16_f32 v2, v68, s0
	global_store_short v[4:5], v2, off offset:2560 nt
	v_cvt_pk_bf16_f32 v2, v69, s0
	global_store_short v[4:5], v2, off offset:2816 nt
	v_cvt_pk_bf16_f32 v2, v70, s0
	global_store_short v[4:5], v2, off offset:3072 nt
	v_cvt_pk_bf16_f32 v2, v71, s0
	global_store_short v[4:5], v2, off offset:3328 nt
	v_cvt_pk_bf16_f32 v2, v26, s0
	global_store_short v[4:5], v2, off offset:3584 nt
	v_cvt_pk_bf16_f32 v2, v72, s0
	global_store_short v[4:5], v2, off offset:3840 nt
	v_lshlrev_b32_e32 v73, 4, v78
